# attention loops: drop per-tile negm tuple copies (use master tuple as SrcC, copy once at loop exit); G1 epilogue: hoist q/k norm gain loads
# speedup vs baseline: 1.0140x; 1.0140x over previous
;     __device__ __forceinline__ void operator()(const f32x4 (&acc)[2][2][4][2], const Unit& u, int wr, int wc, int fr, int fq) const {
;     ...
;         const float* gn = ((ch < 44) ? qn_g : kn_g) + 4 * fq;
;         const float osc = is_q ? ::QSC : 1.0f;
; #pragma unroll
;         for (int ai = 0; ai < 2; ++ai)
; #pragma unroll
;             for (int m = 0; m < 4; ++m) {
;                 const int t = tbase + ai * HALF + m * 16;
;                 float r = osc;
;                 if (do_norm) {
;                     float ss = 0.f;
; #pragma unroll
;                     for (int bj = 0; bj < 2; ++bj)
; #pragma unroll
;                         for (int n = 0; n < 2; ++n)
; #pragma unroll
;                             for (int e = 0; e < 4; ++e) ss += acc[ai][bj][m][n][e] * acc[ai][bj][m][n][e];
;                     ss += __shfl_xor(ss, 16); ss += __shfl_xor(ss, 32);
;                     r *= __builtin_amdgcn_rsqf(ss * (1.0f / 64.0f) + ::LN_EPS);
;                 }
;                 bf16_t* rp = base + (size_t)(toff + t) * 64 + 4 * fq;
; #pragma unroll
;                 for (int bj = 0; bj < 2; ++bj) {
;                     f32x4 lo = acc[ai][bj][m][0] * r, hi2 = acc[ai][bj][m][1] * r;
;                     if (do_norm) { lo = lo * *(const f32x4*)(gn + 32 * bj); hi2 = hi2 * *(const f32x4*)(gn + 32 * bj + 16); }
.LBB0_203:
	v_readlane_b32 s44, v252, 20
	s_cmp_lt_u32 s17, 44
	v_readlane_b32 s54, v252, 30
	v_readlane_b32 s56, v252, 32
	v_readlane_b32 s55, v252, 31
	v_readlane_b32 s57, v252, 33
	s_cselect_b32 s6, s54, s56
	s_cselect_b32 s7, s55, s57
	s_add_u32 s6, s6, s12
	s_addc_u32 s7, s7, s13
	v_lshlrev_b32_e32 v160, 2, v140
	v_cndmask_b32_e64 v153, 0, 1, s[8:9]
	v_lshl_add_u64 v[154:155], s[6:7], 0, v[160:161]
	v_pk_mul_f32 v[130:131], v[74:75], v[158:159] op_sel_hi:[1,0]
	v_pk_mul_f32 v[128:129], v[72:73], v[158:159] op_sel_hi:[1,0]
	v_pk_mul_f32 v[162:163], v[126:127], v[158:159] op_sel_hi:[1,0]
	v_cmp_ne_u32_e64 s[6:7], 1, v153
	s_andn2_b64 vcc, exec, s[8:9]
	v_pk_mul_f32 v[166:167], v[124:125], v[158:159] op_sel_hi:[1,0]
	v_readlane_b32 s45, v252, 21
	v_readlane_b32 s46, v252, 22
	v_readlane_b32 s47, v252, 23
	v_readlane_b32 s48, v252, 24
	v_readlane_b32 s49, v252, 25
	v_readlane_b32 s50, v252, 26
	v_readlane_b32 s51, v252, 27
	v_readlane_b32 s52, v252, 28
	v_readlane_b32 s53, v252, 29
	v_readlane_b32 s58, v252, 34
	v_readlane_b32 s59, v252, 35
	s_cbranch_vccnz .LBB0_205
	global_load_dwordx4 v[208:211], v[154:155], off
	global_load_dwordx4 v[212:215], v[154:155], off offset:64
	global_load_dwordx4 v[228:231], v[154:155], off offset:128
	global_load_dwordx4 v[232:235], v[154:155], off offset:192
	s_waitcnt vmcnt(0)
	v_mov_b64_e32 v[168:169], v[208:209]
	v_mov_b64_e32 v[170:171], v[210:211]
	v_pk_mul_f32 v[130:131], v[130:131], v[170:171]
	v_pk_mul_f32 v[128:129], v[128:129], v[168:169]
	v_mov_b64_e32 v[168:169], v[212:213]
	v_mov_b64_e32 v[170:171], v[214:215]
	v_pk_mul_f32 v[162:163], v[162:163], v[170:171]
	v_pk_mul_f32 v[166:167], v[166:167], v[168:169]

; __device__ __forceinline__ unsigned pk2(float lo, float hi) { f32x2_t v = {lo, hi}; bf16x2_t b = __builtin_convertvector(v, bf16x2_t); return __builtin_bit_cast(unsigned, b); }
;     __device__ __forceinline__ void operator()(const f32x4 (&acc)[2][2][4][2], const Unit& u, int wr, int wc, int fr, int fq) const {
;     ...
;                 bf16_t* rp = base + (size_t)(toff + t) * 64 + 4 * fq;
; #pragma unroll
;                 for (int bj = 0; bj < 2; ++bj) {
;                     f32x4 lo = acc[ai][bj][m][0] * r, hi2 = acc[ai][bj][m][1] * r;
;                     if (do_norm) { lo = lo * *(const f32x4*)(gn + 32 * bj); hi2 = hi2 * *(const f32x4*)(gn + 32 * bj + 16); }
;                     if (!is_ctx) {
;                         const float pos = bj == 0 ? (float)(t >> 6) : (float)(t & 63);
; #pragma unroll
;                         for (int e = 0; e < 4; ++e) { const float th = pos * invf[e]; const float cs = __cosf(th), sn = __sinf(th);
;                             const float a = lo[e], bq = hi2[e]; lo[e] = a * cs - bq * sn; hi2[e] = bq * cs + a * sn; }
;                     }
;                     u32x2 w; w.x = ::pk2(lo[0], lo[1]); w.y = ::pk2(lo[2], lo[3]); *(u32x2*)(rp + 32 * bj) = w;
;                     w.x = ::pk2(hi2[0], hi2[1]); w.y = ::pk2(hi2[2], hi2[3]); *(u32x2*)(rp + 32 * bj + 16) = w;
.LBB0_207:
	v_add_u32_e32 v164, s33, v151
	v_lshlrev_b32_e32 v160, 1, v140
	v_ashrrev_i32_e32 v165, 31, v164
	v_lshl_add_u64 v[156:157], s[28:29], 0, v[160:161]
	v_lshlrev_b64 v[164:165], 7, v[164:165]
	v_readlane_b32 s52, v255, 8
	v_readlane_b32 s54, v255, 10
	v_readlane_b32 s48, v255, 14
	v_readlane_b32 s50, v255, 16
	v_lshl_add_u64 v[164:165], v[156:157], 0, v[164:165]
	v_cvt_pk_bf16_f32 v128, v128, v129
	v_cvt_pk_bf16_f32 v129, v130, v131
	v_readlane_b32 s53, v255, 9
	v_readlane_b32 s55, v255, 11
	v_readlane_b32 s49, v255, 15
	v_readlane_b32 s51, v255, 17
	v_mov_b32_e32 v159, v158
	global_store_dwordx2 v[164:165], v[128:129], off
	v_cvt_pk_bf16_f32 v128, v166, v167
	v_cvt_pk_bf16_f32 v129, v162, v163
	global_store_dwordx2 v[164:165], v[128:129], off offset:32
	v_mov_b32_e32 v162, v158
	v_mov_b32_e32 v163, v158
	v_pk_mul_f32 v[130:131], v[118:119], v[162:163]
	v_pk_mul_f32 v[128:129], v[116:117], v[158:159]
	v_pk_mul_f32 v[162:163], v[114:115], v[162:163]
	s_and_b64 vcc, exec, s[6:7]
	v_pk_mul_f32 v[158:159], v[112:113], v[158:159]
	s_cbranch_vccnz .LBB0_209
	v_mov_b64_e32 v[166:167], v[228:229]
	v_mov_b64_e32 v[168:169], v[230:231]
	v_pk_mul_f32 v[130:131], v[130:131], v[168:169]
	v_pk_mul_f32 v[128:129], v[128:129], v[166:167]
	v_mov_b64_e32 v[166:167], v[232:233]
	v_mov_b64_e32 v[168:169], v[234:235]
	v_pk_mul_f32 v[162:163], v[162:163], v[168:169]
	v_pk_mul_f32 v[158:159], v[158:159], v[166:167]

;     __device__ __forceinline__ void operator()(const f32x4 (&acc)[2][2][4][2], const Unit& u, int wr, int wc, int fr, int fq) const {
;     ...
;                 bf16_t* rp = base + (size_t)(toff + t) * 64 + 4 * fq;
; #pragma unroll
;                 for (int bj = 0; bj < 2; ++bj) {
;                     f32x4 lo = acc[ai][bj][m][0] * r, hi2 = acc[ai][bj][m][1] * r;
;                     if (do_norm) { lo = lo * *(const f32x4*)(gn + 32 * bj); hi2 = hi2 * *(const f32x4*)(gn + 32 * bj + 16); }
.LBB0_213:
	v_pk_mul_f32 v[130:131], v[58:59], v[158:159] op_sel_hi:[1,0]
	v_pk_mul_f32 v[128:129], v[56:57], v[158:159] op_sel_hi:[1,0]
	v_pk_mul_f32 v[164:165], v[122:123], v[158:159] op_sel_hi:[1,0]
	s_and_b64 vcc, exec, s[6:7]
	v_pk_mul_f32 v[166:167], v[120:121], v[158:159] op_sel_hi:[1,0]
	s_cbranch_vccnz .LBB0_215
	v_mov_b64_e32 v[180:181], v[208:209]
	v_mov_b64_e32 v[182:183], v[210:211]
	v_pk_mul_f32 v[130:131], v[130:131], v[182:183]
	v_pk_mul_f32 v[128:129], v[128:129], v[180:181]
	v_mov_b64_e32 v[180:181], v[212:213]
	v_mov_b64_e32 v[182:183], v[214:215]
	v_pk_mul_f32 v[164:165], v[164:165], v[182:183]
	v_pk_mul_f32 v[166:167], v[166:167], v[180:181]

; __device__ __forceinline__ unsigned pk2(float lo, float hi) { f32x2_t v = {lo, hi}; bf16x2_t b = __builtin_convertvector(v, bf16x2_t); return __builtin_bit_cast(unsigned, b); }
;     __device__ __forceinline__ void operator()(const f32x4 (&acc)[2][2][4][2], const Unit& u, int wr, int wc, int fr, int fq) const {
;     ...
;                 bf16_t* rp = base + (size_t)(toff + t) * 64 + 4 * fq;
; #pragma unroll
;                 for (int bj = 0; bj < 2; ++bj) {
;                     f32x4 lo = acc[ai][bj][m][0] * r, hi2 = acc[ai][bj][m][1] * r;
;                     if (do_norm) { lo = lo * *(const f32x4*)(gn + 32 * bj); hi2 = hi2 * *(const f32x4*)(gn + 32 * bj + 16); }
;                     if (!is_ctx) {
;                         const float pos = bj == 0 ? (float)(t >> 6) : (float)(t & 63);
; #pragma unroll
;                         for (int e = 0; e < 4; ++e) { const float th = pos * invf[e]; const float cs = __cosf(th), sn = __sinf(th);
;                             const float a = lo[e], bq = hi2[e]; lo[e] = a * cs - bq * sn; hi2[e] = bq * cs + a * sn; }
;                     }
;                     u32x2 w; w.x = ::pk2(lo[0], lo[1]); w.y = ::pk2(lo[2], lo[3]); *(u32x2*)(rp + 32 * bj) = w;
;                     w.x = ::pk2(hi2[0], hi2[1]); w.y = ::pk2(hi2[2], hi2[3]); *(u32x2*)(rp + 32 * bj + 16) = w;
.LBB0_217:
	v_add_u32_e32 v162, s33, v168
	v_ashrrev_i32_e32 v163, 31, v162
	v_lshlrev_b64 v[162:163], 7, v[162:163]
	v_lshl_add_u64 v[162:163], v[156:157], 0, v[162:163]
	v_cvt_pk_bf16_f32 v128, v128, v129
	v_cvt_pk_bf16_f32 v129, v130, v131
	v_mov_b32_e32 v159, v158
	global_store_dwordx2 v[162:163], v[128:129], off
	v_cvt_pk_bf16_f32 v128, v166, v167
	v_cvt_pk_bf16_f32 v129, v164, v165
	global_store_dwordx2 v[162:163], v[128:129], off offset:32
	v_mov_b32_e32 v164, v158
	v_mov_b32_e32 v165, v158
	v_pk_mul_f32 v[130:131], v[106:107], v[164:165]
	v_pk_mul_f32 v[128:129], v[104:105], v[158:159]
	v_pk_mul_f32 v[164:165], v[102:103], v[164:165]
	s_and_b64 vcc, exec, s[6:7]
	v_pk_mul_f32 v[158:159], v[100:101], v[158:159]
	s_cbranch_vccnz .LBB0_219
	v_mov_b64_e32 v[180:181], v[228:229]
	v_mov_b64_e32 v[182:183], v[230:231]
	v_pk_mul_f32 v[130:131], v[130:131], v[182:183]
	v_pk_mul_f32 v[128:129], v[128:129], v[180:181]
	v_mov_b64_e32 v[180:181], v[232:233]
	v_mov_b64_e32 v[182:183], v[234:235]
	v_pk_mul_f32 v[164:165], v[164:165], v[182:183]
	v_pk_mul_f32 v[158:159], v[158:159], v[180:181]

;     __device__ __forceinline__ void operator()(const f32x4 (&acc)[2][2][4][2], const Unit& u, int wr, int wc, int fr, int fq) const {
;     ...
;                 bf16_t* rp = base + (size_t)(toff + t) * 64 + 4 * fq;
; #pragma unroll
;                 for (int bj = 0; bj < 2; ++bj) {
;                     f32x4 lo = acc[ai][bj][m][0] * r, hi2 = acc[ai][bj][m][1] * r;
;                     if (do_norm) { lo = lo * *(const f32x4*)(gn + 32 * bj); hi2 = hi2 * *(const f32x4*)(gn + 32 * bj + 16); }
.LBB0_223:
	v_pk_mul_f32 v[130:131], v[34:35], v[158:159] op_sel_hi:[1,0]
	v_pk_mul_f32 v[128:129], v[32:33], v[158:159] op_sel_hi:[1,0]
	v_pk_mul_f32 v[164:165], v[110:111], v[158:159] op_sel_hi:[1,0]
	s_and_b64 vcc, exec, s[6:7]
	v_pk_mul_f32 v[166:167], v[108:109], v[158:159] op_sel_hi:[1,0]
	s_cbranch_vccnz .LBB0_225
	v_mov_b64_e32 v[182:183], v[208:209]
	v_mov_b64_e32 v[184:185], v[210:211]
	v_pk_mul_f32 v[130:131], v[130:131], v[184:185]
	v_pk_mul_f32 v[128:129], v[128:129], v[182:183]
	v_mov_b64_e32 v[182:183], v[212:213]
	v_mov_b64_e32 v[184:185], v[214:215]
	v_pk_mul_f32 v[164:165], v[164:165], v[184:185]
	v_pk_mul_f32 v[166:167], v[166:167], v[182:183]

; __device__ __forceinline__ unsigned pk2(float lo, float hi) { f32x2_t v = {lo, hi}; bf16x2_t b = __builtin_convertvector(v, bf16x2_t); return __builtin_bit_cast(unsigned, b); }
;     __device__ __forceinline__ void operator()(const f32x4 (&acc)[2][2][4][2], const Unit& u, int wr, int wc, int fr, int fq) const {
;     ...
;                 bf16_t* rp = base + (size_t)(toff + t) * 64 + 4 * fq;
; #pragma unroll
;                 for (int bj = 0; bj < 2; ++bj) {
;                     f32x4 lo = acc[ai][bj][m][0] * r, hi2 = acc[ai][bj][m][1] * r;
;                     if (do_norm) { lo = lo * *(const f32x4*)(gn + 32 * bj); hi2 = hi2 * *(const f32x4*)(gn + 32 * bj + 16); }
;                     if (!is_ctx) {
;                         const float pos = bj == 0 ? (float)(t >> 6) : (float)(t & 63);
; #pragma unroll
;                         for (int e = 0; e < 4; ++e) { const float th = pos * invf[e]; const float cs = __cosf(th), sn = __sinf(th);
;                             const float a = lo[e], bq = hi2[e]; lo[e] = a * cs - bq * sn; hi2[e] = bq * cs + a * sn; }
;                     }
;                     u32x2 w; w.x = ::pk2(lo[0], lo[1]); w.y = ::pk2(lo[2], lo[3]); *(u32x2*)(rp + 32 * bj) = w;
;                     w.x = ::pk2(hi2[0], hi2[1]); w.y = ::pk2(hi2[2], hi2[3]); *(u32x2*)(rp + 32 * bj + 16) = w;
.LBB0_227:
	v_add_u32_e32 v162, s33, v162
	v_ashrrev_i32_e32 v163, 31, v162
	v_lshlrev_b64 v[162:163], 7, v[162:163]
	v_lshl_add_u64 v[162:163], v[156:157], 0, v[162:163]
	v_cvt_pk_bf16_f32 v128, v128, v129
	v_cvt_pk_bf16_f32 v129, v130, v131
	v_mov_b32_e32 v159, v158
	global_store_dwordx2 v[162:163], v[128:129], off
	v_cvt_pk_bf16_f32 v128, v166, v167
	v_cvt_pk_bf16_f32 v129, v164, v165
	global_store_dwordx2 v[162:163], v[128:129], off offset:32
	v_mov_b32_e32 v164, v158
	v_mov_b32_e32 v165, v158
	v_pk_mul_f32 v[130:131], v[94:95], v[164:165]
	v_pk_mul_f32 v[128:129], v[92:93], v[158:159]
	v_pk_mul_f32 v[164:165], v[90:91], v[164:165]
	s_and_b64 vcc, exec, s[6:7]
	v_pk_mul_f32 v[158:159], v[88:89], v[158:159]
	s_cbranch_vccnz .LBB0_229
	v_mov_b64_e32 v[182:183], v[228:229]
	v_mov_b64_e32 v[184:185], v[230:231]
	v_pk_mul_f32 v[130:131], v[130:131], v[184:185]
	v_pk_mul_f32 v[128:129], v[128:129], v[182:183]
	v_mov_b64_e32 v[182:183], v[232:233]
	v_mov_b64_e32 v[184:185], v[234:235]
	v_pk_mul_f32 v[164:165], v[164:165], v[184:185]
	v_pk_mul_f32 v[158:159], v[158:159], v[182:183]

;     __device__ __forceinline__ void operator()(const f32x4 (&acc)[2][2][4][2], const Unit& u, int wr, int wc, int fr, int fq) const {
;     ...
;                 bf16_t* rp = base + (size_t)(toff + t) * 64 + 4 * fq;
; #pragma unroll
;                 for (int bj = 0; bj < 2; ++bj) {
;                     f32x4 lo = acc[ai][bj][m][0] * r, hi2 = acc[ai][bj][m][1] * r;
;                     if (do_norm) { lo = lo * *(const f32x4*)(gn + 32 * bj); hi2 = hi2 * *(const f32x4*)(gn + 32 * bj + 16); }
.LBB0_233:
	v_pk_mul_f32 v[130:131], v[18:19], v[158:159] op_sel_hi:[1,0]
	v_pk_mul_f32 v[128:129], v[16:17], v[158:159] op_sel_hi:[1,0]
	v_pk_mul_f32 v[164:165], v[98:99], v[158:159] op_sel_hi:[1,0]
	s_and_b64 vcc, exec, s[6:7]
	v_pk_mul_f32 v[166:167], v[96:97], v[158:159] op_sel_hi:[1,0]
	s_cbranch_vccnz .LBB0_235
	v_mov_b64_e32 v[186:187], v[208:209]
	v_mov_b64_e32 v[188:189], v[210:211]
	v_pk_mul_f32 v[130:131], v[130:131], v[188:189]
	v_pk_mul_f32 v[128:129], v[128:129], v[186:187]
	v_mov_b64_e32 v[186:187], v[212:213]
	v_mov_b64_e32 v[188:189], v[214:215]
	v_pk_mul_f32 v[164:165], v[164:165], v[188:189]
	v_pk_mul_f32 v[166:167], v[166:167], v[186:187]

; __device__ __forceinline__ unsigned pk2(float lo, float hi) { f32x2_t v = {lo, hi}; bf16x2_t b = __builtin_convertvector(v, bf16x2_t); return __builtin_bit_cast(unsigned, b); }
;     __device__ __forceinline__ void operator()(const f32x4 (&acc)[2][2][4][2], const Unit& u, int wr, int wc, int fr, int fq) const {
;     ...
;                 bf16_t* rp = base + (size_t)(toff + t) * 64 + 4 * fq;
; #pragma unroll
;                 for (int bj = 0; bj < 2; ++bj) {
;                     f32x4 lo = acc[ai][bj][m][0] * r, hi2 = acc[ai][bj][m][1] * r;
;                     if (do_norm) { lo = lo * *(const f32x4*)(gn + 32 * bj); hi2 = hi2 * *(const f32x4*)(gn + 32 * bj + 16); }
;                     if (!is_ctx) {
;                         const float pos = bj == 0 ? (float)(t >> 6) : (float)(t & 63);
; #pragma unroll
;                         for (int e = 0; e < 4; ++e) { const float th = pos * invf[e]; const float cs = __cosf(th), sn = __sinf(th);
;                             const float a = lo[e], bq = hi2[e]; lo[e] = a * cs - bq * sn; hi2[e] = bq * cs + a * sn; }
;                     }
;                     u32x2 w; w.x = ::pk2(lo[0], lo[1]); w.y = ::pk2(lo[2], lo[3]); *(u32x2*)(rp + 32 * bj) = w;
;                     w.x = ::pk2(hi2[0], hi2[1]); w.y = ::pk2(hi2[2], hi2[3]); *(u32x2*)(rp + 32 * bj + 16) = w;
.LBB0_237:
	v_add_u32_e32 v162, s33, v182
	v_ashrrev_i32_e32 v163, 31, v162
	v_lshlrev_b64 v[162:163], 7, v[162:163]
	v_lshl_add_u64 v[162:163], v[156:157], 0, v[162:163]
	v_cvt_pk_bf16_f32 v128, v128, v129
	v_cvt_pk_bf16_f32 v129, v130, v131
	v_mov_b32_e32 v159, v158
	global_store_dwordx2 v[162:163], v[128:129], off
	v_cvt_pk_bf16_f32 v128, v166, v167
	v_cvt_pk_bf16_f32 v129, v164, v165
	global_store_dwordx2 v[162:163], v[128:129], off offset:32
	v_mov_b32_e32 v164, v158
	v_mov_b32_e32 v165, v158
	v_pk_mul_f32 v[130:131], v[86:87], v[164:165]
	v_pk_mul_f32 v[128:129], v[84:85], v[158:159]
	v_pk_mul_f32 v[164:165], v[82:83], v[164:165]
	s_and_b64 vcc, exec, s[6:7]
	v_pk_mul_f32 v[158:159], v[80:81], v[158:159]
	s_cbranch_vccnz .LBB0_239
	v_mov_b64_e32 v[186:187], v[228:229]
	v_mov_b64_e32 v[188:189], v[230:231]
	v_pk_mul_f32 v[130:131], v[130:131], v[188:189]
	v_pk_mul_f32 v[128:129], v[128:129], v[186:187]
	v_mov_b64_e32 v[186:187], v[232:233]
	v_mov_b64_e32 v[188:189], v[234:235]
	v_pk_mul_f32 v[164:165], v[164:165], v[188:189]
	v_pk_mul_f32 v[158:159], v[158:159], v[186:187]

;     __device__ __forceinline__ void operator()(const f32x4 (&acc)[2][2][4][2], const Unit& u, int wr, int wc, int fr, int fq) const {
;     ...
;                 bf16_t* rp = base + (size_t)(toff + t) * 64 + 4 * fq;
; #pragma unroll
;                 for (int bj = 0; bj < 2; ++bj) {
;                     f32x4 lo = acc[ai][bj][m][0] * r, hi2 = acc[ai][bj][m][1] * r;
;                     if (do_norm) { lo = lo * *(const f32x4*)(gn + 32 * bj); hi2 = hi2 * *(const f32x4*)(gn + 32 * bj + 16); }
.LBB0_243:
	v_pk_mul_f32 v[130:131], v[14:15], v[158:159] op_sel_hi:[1,0]
	v_pk_mul_f32 v[128:129], v[12:13], v[158:159] op_sel_hi:[1,0]
	v_pk_mul_f32 v[164:165], v[78:79], v[158:159] op_sel_hi:[1,0]
	s_and_b64 vcc, exec, s[6:7]
	v_pk_mul_f32 v[166:167], v[76:77], v[158:159] op_sel_hi:[1,0]
	s_cbranch_vccnz .LBB0_245
	v_mov_b64_e32 v[200:201], v[208:209]
	v_mov_b64_e32 v[202:203], v[210:211]
	v_pk_mul_f32 v[130:131], v[130:131], v[202:203]
	v_pk_mul_f32 v[128:129], v[128:129], v[200:201]
	v_mov_b64_e32 v[200:201], v[212:213]
	v_mov_b64_e32 v[202:203], v[214:215]
	v_pk_mul_f32 v[164:165], v[164:165], v[202:203]
	v_pk_mul_f32 v[166:167], v[166:167], v[200:201]

; __device__ __forceinline__ unsigned pk2(float lo, float hi) { f32x2_t v = {lo, hi}; bf16x2_t b = __builtin_convertvector(v, bf16x2_t); return __builtin_bit_cast(unsigned, b); }
;     __device__ __forceinline__ void operator()(const f32x4 (&acc)[2][2][4][2], const Unit& u, int wr, int wc, int fr, int fq) const {
;     ...
;                 bf16_t* rp = base + (size_t)(toff + t) * 64 + 4 * fq;
; #pragma unroll
;                 for (int bj = 0; bj < 2; ++bj) {
;                     f32x4 lo = acc[ai][bj][m][0] * r, hi2 = acc[ai][bj][m][1] * r;
;                     if (do_norm) { lo = lo * *(const f32x4*)(gn + 32 * bj); hi2 = hi2 * *(const f32x4*)(gn + 32 * bj + 16); }
;                     if (!is_ctx) {
;                         const float pos = bj == 0 ? (float)(t >> 6) : (float)(t & 63);
; #pragma unroll
;                         for (int e = 0; e < 4; ++e) { const float th = pos * invf[e]; const float cs = __cosf(th), sn = __sinf(th);
;                             const float a = lo[e], bq = hi2[e]; lo[e] = a * cs - bq * sn; hi2[e] = bq * cs + a * sn; }
;                     }
;                     u32x2 w; w.x = ::pk2(lo[0], lo[1]); w.y = ::pk2(lo[2], lo[3]); *(u32x2*)(rp + 32 * bj) = w;
;                     w.x = ::pk2(hi2[0], hi2[1]); w.y = ::pk2(hi2[2], hi2[3]); *(u32x2*)(rp + 32 * bj + 16) = w;
.LBB0_247:
	v_add_u32_e32 v162, s33, v162
	v_ashrrev_i32_e32 v163, 31, v162
	v_lshlrev_b64 v[162:163], 7, v[162:163]
	v_lshl_add_u64 v[162:163], v[156:157], 0, v[162:163]
	v_cvt_pk_bf16_f32 v128, v128, v129
	v_cvt_pk_bf16_f32 v129, v130, v131
	v_mov_b32_e32 v159, v158
	global_store_dwordx2 v[162:163], v[128:129], off
	v_cvt_pk_bf16_f32 v128, v166, v167
	v_cvt_pk_bf16_f32 v129, v164, v165
	global_store_dwordx2 v[162:163], v[128:129], off offset:32
	v_mov_b32_e32 v164, v158
	v_mov_b32_e32 v165, v158
	v_pk_mul_f32 v[130:131], v[66:67], v[164:165]
	v_pk_mul_f32 v[128:129], v[64:65], v[158:159]
	v_pk_mul_f32 v[164:165], v[62:63], v[164:165]
	s_and_b64 vcc, exec, s[6:7]
	v_pk_mul_f32 v[158:159], v[60:61], v[158:159]
	s_cbranch_vccnz .LBB0_249
	v_mov_b64_e32 v[200:201], v[228:229]
	v_mov_b64_e32 v[202:203], v[230:231]
	v_pk_mul_f32 v[130:131], v[130:131], v[202:203]
	v_pk_mul_f32 v[128:129], v[128:129], v[200:201]
	v_mov_b64_e32 v[200:201], v[232:233]
	v_mov_b64_e32 v[202:203], v[234:235]
	v_pk_mul_f32 v[164:165], v[164:165], v[202:203]
	v_pk_mul_f32 v[158:159], v[158:159], v[200:201]

;     __device__ __forceinline__ void operator()(const f32x4 (&acc)[2][2][4][2], const Unit& u, int wr, int wc, int fr, int fq) const {
;     ...
;                 bf16_t* rp = base + (size_t)(toff + t) * 64 + 4 * fq;
; #pragma unroll
;                 for (int bj = 0; bj < 2; ++bj) {
;                     f32x4 lo = acc[ai][bj][m][0] * r, hi2 = acc[ai][bj][m][1] * r;
;                     if (do_norm) { lo = lo * *(const f32x4*)(gn + 32 * bj); hi2 = hi2 * *(const f32x4*)(gn + 32 * bj + 16); }
.LBB0_253:
	v_pk_mul_f32 v[130:131], v[10:11], v[158:159] op_sel_hi:[1,0]
	v_pk_mul_f32 v[128:129], v[8:9], v[158:159] op_sel_hi:[1,0]
	v_pk_mul_f32 v[164:165], v[70:71], v[158:159] op_sel_hi:[1,0]
	s_and_b64 vcc, exec, s[6:7]
	v_pk_mul_f32 v[166:167], v[68:69], v[158:159] op_sel_hi:[1,0]
	s_cbranch_vccnz .LBB0_255
	v_mov_b64_e32 v[200:201], v[208:209]
	v_mov_b64_e32 v[202:203], v[210:211]
	v_pk_mul_f32 v[130:131], v[130:131], v[202:203]
	v_pk_mul_f32 v[128:129], v[128:129], v[200:201]
	v_mov_b64_e32 v[200:201], v[212:213]
	v_mov_b64_e32 v[202:203], v[214:215]
	v_pk_mul_f32 v[164:165], v[164:165], v[202:203]
	v_pk_mul_f32 v[166:167], v[166:167], v[200:201]

; __device__ __forceinline__ unsigned pk2(float lo, float hi) { f32x2_t v = {lo, hi}; bf16x2_t b = __builtin_convertvector(v, bf16x2_t); return __builtin_bit_cast(unsigned, b); }
;     __device__ __forceinline__ void operator()(const f32x4 (&acc)[2][2][4][2], const Unit& u, int wr, int wc, int fr, int fq) const {
;     ...
;                 bf16_t* rp = base + (size_t)(toff + t) * 64 + 4 * fq;
; #pragma unroll
;                 for (int bj = 0; bj < 2; ++bj) {
;                     f32x4 lo = acc[ai][bj][m][0] * r, hi2 = acc[ai][bj][m][1] * r;
;                     if (do_norm) { lo = lo * *(const f32x4*)(gn + 32 * bj); hi2 = hi2 * *(const f32x4*)(gn + 32 * bj + 16); }
;                     if (!is_ctx) {
;                         const float pos = bj == 0 ? (float)(t >> 6) : (float)(t & 63);
; #pragma unroll
;                         for (int e = 0; e < 4; ++e) { const float th = pos * invf[e]; const float cs = __cosf(th), sn = __sinf(th);
;                             const float a = lo[e], bq = hi2[e]; lo[e] = a * cs - bq * sn; hi2[e] = bq * cs + a * sn; }
;                     }
;                     u32x2 w; w.x = ::pk2(lo[0], lo[1]); w.y = ::pk2(lo[2], lo[3]); *(u32x2*)(rp + 32 * bj) = w;
;                     w.x = ::pk2(hi2[0], hi2[1]); w.y = ::pk2(hi2[2], hi2[3]); *(u32x2*)(rp + 32 * bj + 16) = w;
.LBB0_257:
	v_add_u32_e32 v162, s33, v153
	v_ashrrev_i32_e32 v163, 31, v162
	v_lshlrev_b64 v[162:163], 7, v[162:163]
	v_lshl_add_u64 v[162:163], v[156:157], 0, v[162:163]
	v_cvt_pk_bf16_f32 v128, v128, v129
	v_cvt_pk_bf16_f32 v129, v130, v131
	v_mov_b32_e32 v159, v158
	global_store_dwordx2 v[162:163], v[128:129], off
	v_cvt_pk_bf16_f32 v128, v166, v167
	v_cvt_pk_bf16_f32 v129, v164, v165
	global_store_dwordx2 v[162:163], v[128:129], off offset:32
	v_mov_b32_e32 v164, v158
	v_mov_b32_e32 v165, v158
	v_pk_mul_f32 v[130:131], v[50:51], v[164:165]
	v_pk_mul_f32 v[128:129], v[48:49], v[158:159]
	v_pk_mul_f32 v[164:165], v[46:47], v[164:165]
	s_and_b64 vcc, exec, s[6:7]
	v_pk_mul_f32 v[158:159], v[44:45], v[158:159]
	s_cbranch_vccnz .LBB0_259
	v_mov_b64_e32 v[200:201], v[228:229]
	v_mov_b64_e32 v[202:203], v[230:231]
	v_pk_mul_f32 v[130:131], v[130:131], v[202:203]
	v_pk_mul_f32 v[128:129], v[128:129], v[200:201]
	v_mov_b64_e32 v[200:201], v[232:233]
	v_mov_b64_e32 v[202:203], v[234:235]
	v_pk_mul_f32 v[164:165], v[164:165], v[202:203]
	v_pk_mul_f32 v[158:159], v[158:159], v[200:201]

;     __device__ __forceinline__ void operator()(const f32x4 (&acc)[2][2][4][2], const Unit& u, int wr, int wc, int fr, int fq) const {
;     ...
;                 bf16_t* rp = base + (size_t)(toff + t) * 64 + 4 * fq;
; #pragma unroll
;                 for (int bj = 0; bj < 2; ++bj) {
;                     f32x4 lo = acc[ai][bj][m][0] * r, hi2 = acc[ai][bj][m][1] * r;
;                     if (do_norm) { lo = lo * *(const f32x4*)(gn + 32 * bj); hi2 = hi2 * *(const f32x4*)(gn + 32 * bj + 16); }
.LBB0_263:
	v_pk_mul_f32 v[130:131], v[6:7], v[158:159] op_sel_hi:[1,0]
	v_pk_mul_f32 v[128:129], v[4:5], v[158:159] op_sel_hi:[1,0]
	v_pk_mul_f32 v[164:165], v[54:55], v[158:159] op_sel_hi:[1,0]
	s_and_b64 vcc, exec, s[6:7]
	v_pk_mul_f32 v[166:167], v[52:53], v[158:159] op_sel_hi:[1,0]
	s_cbranch_vccnz .LBB0_265
	v_mov_b64_e32 v[168:169], v[208:209]
	v_mov_b64_e32 v[170:171], v[210:211]
	v_pk_mul_f32 v[130:131], v[130:131], v[170:171]
	v_pk_mul_f32 v[128:129], v[128:129], v[168:169]
	v_mov_b64_e32 v[168:169], v[212:213]
	v_mov_b64_e32 v[170:171], v[214:215]
	v_pk_mul_f32 v[164:165], v[164:165], v[170:171]
	v_pk_mul_f32 v[166:167], v[166:167], v[168:169]

; __device__ __forceinline__ unsigned pk2(float lo, float hi) { f32x2_t v = {lo, hi}; bf16x2_t b = __builtin_convertvector(v, bf16x2_t); return __builtin_bit_cast(unsigned, b); }
;     __device__ __forceinline__ void operator()(const f32x4 (&acc)[2][2][4][2], const Unit& u, int wr, int wc, int fr, int fq) const {
;     ...
;                 bf16_t* rp = base + (size_t)(toff + t) * 64 + 4 * fq;
; #pragma unroll
;                 for (int bj = 0; bj < 2; ++bj) {
;                     f32x4 lo = acc[ai][bj][m][0] * r, hi2 = acc[ai][bj][m][1] * r;
;                     if (do_norm) { lo = lo * *(const f32x4*)(gn + 32 * bj); hi2 = hi2 * *(const f32x4*)(gn + 32 * bj + 16); }
;                     if (!is_ctx) {
;                         const float pos = bj == 0 ? (float)(t >> 6) : (float)(t & 63);
; #pragma unroll
;                         for (int e = 0; e < 4; ++e) { const float th = pos * invf[e]; const float cs = __cosf(th), sn = __sinf(th);
;                             const float a = lo[e], bq = hi2[e]; lo[e] = a * cs - bq * sn; hi2[e] = bq * cs + a * sn; }
;                     }
;                     u32x2 w; w.x = ::pk2(lo[0], lo[1]); w.y = ::pk2(lo[2], lo[3]); *(u32x2*)(rp + 32 * bj) = w;
;                     w.x = ::pk2(hi2[0], hi2[1]); w.y = ::pk2(hi2[2], hi2[3]); *(u32x2*)(rp + 32 * bj + 16) = w;
.LBB0_267:
	v_add_u32_e32 v162, s33, v153
	v_ashrrev_i32_e32 v163, 31, v162
	v_lshlrev_b64 v[162:163], 7, v[162:163]
	v_lshl_add_u64 v[162:163], v[156:157], 0, v[162:163]
	v_cvt_pk_bf16_f32 v128, v128, v129
	v_cvt_pk_bf16_f32 v129, v130, v131
	v_mov_b32_e32 v159, v158
	global_store_dwordx2 v[162:163], v[128:129], off
	v_cvt_pk_bf16_f32 v128, v166, v167
	v_cvt_pk_bf16_f32 v129, v164, v165
	global_store_dwordx2 v[162:163], v[128:129], off offset:32
	v_mov_b32_e32 v164, v158
	v_mov_b32_e32 v165, v158
	v_pk_mul_f32 v[130:131], v[38:39], v[164:165]
	v_pk_mul_f32 v[128:129], v[36:37], v[158:159]
	v_pk_mul_f32 v[164:165], v[30:31], v[164:165]
	s_and_b64 vcc, exec, s[6:7]
	v_pk_mul_f32 v[158:159], v[28:29], v[158:159]
	s_cbranch_vccnz .LBB0_269
	v_mov_b64_e32 v[166:167], v[228:229]
	v_mov_b64_e32 v[168:169], v[230:231]
	v_pk_mul_f32 v[130:131], v[130:131], v[168:169]
	v_pk_mul_f32 v[128:129], v[128:129], v[166:167]
	v_mov_b64_e32 v[166:167], v[232:233]
	v_mov_b64_e32 v[168:169], v[234:235]
	v_pk_mul_f32 v[164:165], v[164:165], v[168:169]
	v_pk_mul_f32 v[158:159], v[158:159], v[166:167]

;     __device__ __forceinline__ void operator()(const f32x4 (&acc)[2][2][4][2], const Unit& u, int wr, int wc, int fr, int fq) const {
;     ...
;                 bf16_t* rp = base + (size_t)(toff + t) * 64 + 4 * fq;
; #pragma unroll
;                 for (int bj = 0; bj < 2; ++bj) {
;                     f32x4 lo = acc[ai][bj][m][0] * r, hi2 = acc[ai][bj][m][1] * r;
;                     if (do_norm) { lo = lo * *(const f32x4*)(gn + 32 * bj); hi2 = hi2 * *(const f32x4*)(gn + 32 * bj + 16); }
.LBB0_273:
	v_pk_mul_f32 v[130:131], v[2:3], v[152:153] op_sel_hi:[1,0]
	v_pk_mul_f32 v[128:129], v[0:1], v[152:153] op_sel_hi:[1,0]
	v_pk_mul_f32 v[158:159], v[42:43], v[152:153] op_sel_hi:[1,0]
	s_and_b64 vcc, exec, s[6:7]
	v_pk_mul_f32 v[162:163], v[40:41], v[152:153] op_sel_hi:[1,0]
	s_cbranch_vccnz .LBB0_275
	v_mov_b64_e32 v[164:165], v[208:209]
	v_mov_b64_e32 v[166:167], v[210:211]
	v_pk_mul_f32 v[130:131], v[130:131], v[166:167]
	v_pk_mul_f32 v[128:129], v[128:129], v[164:165]
	v_mov_b64_e32 v[164:165], v[212:213]
	v_mov_b64_e32 v[166:167], v[214:215]
	v_pk_mul_f32 v[158:159], v[158:159], v[166:167]
	v_pk_mul_f32 v[162:163], v[162:163], v[164:165]

; __device__ __forceinline__ unsigned pk2(float lo, float hi) { f32x2_t v = {lo, hi}; bf16x2_t b = __builtin_convertvector(v, bf16x2_t); return __builtin_bit_cast(unsigned, b); }
;     __device__ __forceinline__ void operator()(const f32x4 (&acc)[2][2][4][2], const Unit& u, int wr, int wc, int fr, int fq) const {
;     ...
;                 bf16_t* rp = base + (size_t)(toff + t) * 64 + 4 * fq;
; #pragma unroll
;                 for (int bj = 0; bj < 2; ++bj) {
;                     f32x4 lo = acc[ai][bj][m][0] * r, hi2 = acc[ai][bj][m][1] * r;
;                     if (do_norm) { lo = lo * *(const f32x4*)(gn + 32 * bj); hi2 = hi2 * *(const f32x4*)(gn + 32 * bj + 16); }
;                     if (!is_ctx) {
;                         const float pos = bj == 0 ? (float)(t >> 6) : (float)(t & 63);
; #pragma unroll
;                         for (int e = 0; e < 4; ++e) { const float th = pos * invf[e]; const float cs = __cosf(th), sn = __sinf(th);
;                             const float a = lo[e], bq = hi2[e]; lo[e] = a * cs - bq * sn; hi2[e] = bq * cs + a * sn; }
;                     }
;                     u32x2 w; w.x = ::pk2(lo[0], lo[1]); w.y = ::pk2(lo[2], lo[3]); *(u32x2*)(rp + 32 * bj) = w;
;                     w.x = ::pk2(hi2[0], hi2[1]); w.y = ::pk2(hi2[2], hi2[3]); *(u32x2*)(rp + 32 * bj + 16) = w;
.LBB0_277:
	v_add_u32_e32 v164, s33, v160
	v_ashrrev_i32_e32 v165, 31, v164
	v_lshlrev_b64 v[164:165], 7, v[164:165]
	v_lshl_add_u64 v[156:157], v[156:157], 0, v[164:165]
	v_cvt_pk_bf16_f32 v128, v128, v129
	v_cvt_pk_bf16_f32 v129, v130, v131
	v_mov_b32_e32 v153, v152
	global_store_dwordx2 v[156:157], v[128:129], off
	v_cvt_pk_bf16_f32 v128, v162, v163
	v_cvt_pk_bf16_f32 v129, v158, v159
	global_store_dwordx2 v[156:157], v[128:129], off offset:32
	v_mov_b32_e32 v158, v152
	v_mov_b32_e32 v159, v152
	v_pk_mul_f32 v[130:131], v[26:27], v[158:159]
	v_pk_mul_f32 v[128:129], v[24:25], v[152:153]
	v_pk_mul_f32 v[158:159], v[22:23], v[158:159]
	s_and_b64 vcc, exec, s[6:7]
	v_pk_mul_f32 v[152:153], v[20:21], v[152:153]
	s_cbranch_vccnz .LBB0_279
	v_mov_b64_e32 v[162:163], v[228:229]
	v_mov_b64_e32 v[164:165], v[230:231]
	v_pk_mul_f32 v[130:131], v[130:131], v[164:165]
	v_pk_mul_f32 v[128:129], v[128:129], v[162:163]
	v_mov_b64_e32 v[162:163], v[232:233]
	v_mov_b64_e32 v[164:165], v[234:235]
	v_pk_mul_f32 v[158:159], v[158:159], v[164:165]
	v_pk_mul_f32 v[152:153], v[152:153], v[162:163]

; template <int DV, int PAR, bool KW = true, bool KL = true, bool VL = true>
; __device__ __forceinline__ void attn_iter_full(AttnState<DV>& S, int t, LAS unsigned char* lds) {
;     ...
;     f32x16& C0 = PAR ? S.sd0 : S.sc0; f32x16& C1 = PAR ? S.sd1 : S.sc1; f32x16& sn0 = PAR ? S.sc0 : S.sd0; f32x16& sn1 = PAR ? S.sc1 : S.sd1;
;     sn0 = S.negm; sn1 = S.negm;
;     u32x4 pw[4]; float mxa = 0.f, mxb = 0.f, mx = 0.f; f32x16 ssum;
;     constexpr int PD = (DV == 64) ? 3 : 2; bf16x8 fr[PD + 1];
;     ...
; #pragma unroll
;     for (int i = 0; i < PD; ++i) fr[i] = AT_FRAG(i);
;     __builtin_amdgcn_sched_barrier(0);
; #pragma unroll
;     for (int i = 0; i < NS; ++i) {
;         if (i + PD < NS) fr[(i + PD) % (PD + 1)] = AT_FRAG(i + PD);
;         if (i == 3) {
;             if (KW) *(LAS u32x4*)(lds + AT_K0 + PAR * AT_KB + S.kl) = S.kreg;
;             LAS unsigned char* W = lds + AT_V0 + (PAR ^ 1) * AT_VB + S.vl; *(LAS u32x4*)W = S.vreg0; if (DV == 128) *(LAS u32x4*)(W + 64 * 144) = S.vreg1; }
;         if (i == 5) { if (KL) S.kreg = *(const u32x4*)(S.kg + (size_t)(t + 3) * 4096);
;             if (VL) { S.vreg0 = *(const u32x4*)(S.vg + (t + 2) * 64); if (DV == 128) S.vreg1 = *(const u32x4*)(S.vg + (size_t)64 * TK + (t + 2) * 64); } }
;         if (i < 8) { if (i & 1) sn1 = MFMA32(fr[i % (PD + 1)], S.qr[i >> 1], sn1); else sn0 = MFMA32(fr[i % (PD + 1)], S.qr[i >> 1], sn0); }
;         else { const int j = i - 8; S.o[j % NDB] = MFMA32(fr[i % (PD + 1)], __builtin_bit_cast(bf16x8, pw[j / NDB]), S.o[j % NDB]); }
; #pragma unroll
;         for (int u = 0; u < NU; ++u) {
;             if (u * NS / NU != i) continue;
;             if (u < 20) {
;                 const int q = u / 5, r = u % 5;
;                 if (r < 4) { const int e = 8 * q + 2 * r;
;                     if (e < 16) { C0[e] = fast_exp2(C0[e]); C0[e + 1] = fast_exp2(C0[e + 1]); }
;                     else { C1[e - 16] = fast_exp2(C1[e - 16]); C1[e - 15] = fast_exp2(C1[e - 15]); } }
;                 else { if (q < 2) { const int b0 = 8 * q; pw[q].x = pk2(C0[b0], C0[b0 + 1]); pw[q].y = pk2(C0[b0 + 2], C0[b0 + 3]); pw[q].z = pk2(C0[b0 + 4], C0[b0 + 5]); pw[q].w = pk2(C0[b0 + 6], C0[b0 + 7]); }
;                        else { const int b0 = 8 * (q - 2); pw[q].x = pk2(C1[b0], C1[b0 + 1]); pw[q].y = pk2(C1[b0 + 2], C1[b0 + 3]); pw[q].z = pk2(C1[b0 + 4], C1[b0 + 5]); pw[q].w = pk2(C1[b0 + 6], C1[b0 + 7]); } }
.LBB0_399:
.LBB0_400:
	s_barrier
	ds_read_b128 v[48:51], v169
	ds_read_b128 v[172:175], v169 offset:4608
	ds_read_b128 v[176:179], v169 offset:32
	s_waitcnt lgkmcnt(2)
	v_mfma_f32_32x32x16_bf16 v[80:95], v[48:51], v[140:143], v[64:79]
	ds_read_b128 v[180:183], v169 offset:4640
	v_exp_f32_e32 v184, v112
	v_exp_f32_e32 v185, v113
	v_exp_f32_e32 v186, v114
	v_exp_f32_e32 v187, v115
	s_waitcnt lgkmcnt(2)
	v_mfma_f32_32x32x16_bf16 v[48:63], v[172:175], v[140:143], v[64:79]
	ds_read_b128 v[112:115], v169 offset:64
	v_exp_f32_e32 v188, v116
	v_exp_f32_e32 v189, v117
	v_exp_f32_e32 v190, v118
	v_exp_f32_e32 v191, v119
	s_waitcnt lgkmcnt(2)
	v_mfma_f32_32x32x16_bf16 v[80:95], v[176:179], v[136:139], v[80:95]
	ds_read_b128 v[116:119], v169 offset:4672
	v_cvt_pk_bf16_f32 v172, v184, v185
	v_cvt_pk_bf16_f32 v173, v186, v187
	v_cvt_pk_bf16_f32 v174, v188, v189
	v_cvt_pk_bf16_f32 v175, v190, v191
	v_exp_f32_e32 v192, v120
	v_exp_f32_e32 v193, v121
	s_waitcnt lgkmcnt(2)
	v_mfma_f32_32x32x16_bf16 v[48:63], v[180:183], v[136:139], v[48:63]
	ds_read_b128 v[176:179], v169 offset:96
	s_waitcnt vmcnt(1)
	ds_write_b128 v168, v[144:147] offset:9216
	s_waitcnt vmcnt(0)
	ds_write_b128 v168, v[148:151] offset:18432
	v_exp_f32_e32 v196, v122
	v_exp_f32_e32 v197, v123
	s_waitcnt lgkmcnt(4)
	v_mfma_f32_32x32x16_bf16 v[80:95], v[112:115], v[132:135], v[80:95]
	ds_read_b128 v[120:123], v169 offset:4704
	v_exp_f32_e32 v180, v124
	v_exp_f32_e32 v181, v125
	v_exp_f32_e32 v182, v126
	v_exp_f32_e32 v183, v127
	s_mov_b32 s4, 0x16308000
	v_add_co_u32_e32 v124, vcc, s4, v162
	ds_read_b128 v[112:115], v167 offset:36864
	s_nop 0
	v_addc_co_u32_e32 v125, vcc, 0, v163, vcc
	global_load_dwordx4 v[144:147], v[124:125], off
	global_load_dwordx4 v[148:151], v[164:165], off offset:384
	s_waitcnt lgkmcnt(5)
	v_mfma_f32_32x32x16_bf16 v[48:63], v[116:119], v[132:135], v[48:63]
	v_cvt_pk_bf16_f32 v116, v192, v193
	v_exp_f32_e32 v162, v96
	v_exp_f32_e32 v163, v97
	v_cvt_pk_bf16_f32 v117, v196, v197
	v_cvt_pk_bf16_f32 v118, v180, v181
	v_cvt_pk_bf16_f32 v119, v182, v183
	s_waitcnt lgkmcnt(4)
	v_mfma_f32_32x32x16_bf16 v[80:95], v[176:179], v[128:131], v[80:95]
	ds_read_b128 v[124:127], v167 offset:41472
	v_exp_f32_e32 v164, v98
	v_exp_f32_e32 v165, v99
	s_waitcnt lgkmcnt(2)
	v_mfma_f32_32x32x16_bf16 v[48:63], v[120:123], v[128:131], v[48:63]
	ds_read_b128 v[96:99], v167 offset:36896
	v_exp_f32_e32 v176, v100
	v_exp_f32_e32 v177, v101
	v_exp_f32_e32 v178, v102
	v_exp_f32_e32 v179, v103
	s_waitcnt lgkmcnt(2)
	v_mfma_f32_32x32x16_bf16 v[0:15], v[112:115], v[172:175], v[0:15]
	ds_read_b128 v[100:103], v167 offset:41504
	v_cvt_pk_bf16_f32 v112, v162, v163
	v_cvt_pk_bf16_f32 v113, v164, v165
	v_cvt_pk_bf16_f32 v114, v176, v177
	v_cvt_pk_bf16_f32 v115, v178, v179
	v_exp_f32_e32 v198, v104
	v_exp_f32_e32 v199, v105
	s_waitcnt lgkmcnt(2)
	v_mfma_f32_32x32x16_bf16 v[16:31], v[124:127], v[172:175], v[16:31]
	ds_read_b128 v[120:123], v167 offset:36928
	v_exp_f32_e32 v124, v106
	v_exp_f32_e32 v125, v107
	s_waitcnt lgkmcnt(2)
	v_mfma_f32_32x32x16_bf16 v[0:15], v[96:99], v[116:119], v[0:15]
	ds_read_b128 v[104:107], v167 offset:41536
	v_exp_f32_e32 v108, v108
	v_exp_f32_e32 v109, v109
	v_exp_f32_e32 v110, v110
	v_exp_f32_e32 v111, v111
	s_waitcnt lgkmcnt(2)
	v_mfma_f32_32x32x16_bf16 v[16:31], v[100:103], v[116:119], v[16:31]
	ds_read_b128 v[96:99], v167 offset:36960
	v_cvt_pk_bf16_f32 v100, v198, v199
	v_cvt_pk_bf16_f32 v101, v124, v125
	v_cvt_pk_bf16_f32 v102, v108, v109
	v_cvt_pk_bf16_f32 v103, v110, v111
	v_pk_add_f32 v[116:117], v[108:109], v[180:181]
	v_pk_add_f32 v[118:119], v[110:111], v[182:183]
	v_pk_add_f32 v[124:125], v[124:125], v[196:197]
	v_pk_add_f32 v[126:127], v[198:199], v[192:193]
	v_pk_add_f32 v[172:173], v[176:177], v[188:189]
	v_pk_add_f32 v[162:163], v[162:163], v[184:185]
	v_pk_add_f32 v[174:175], v[178:179], v[190:191]
	v_pk_add_f32 v[164:165], v[164:165], v[186:187]
	s_waitcnt lgkmcnt(2)
	v_mfma_f32_32x32x16_bf16 v[0:15], v[120:123], v[112:115], v[0:15]
	v_add_f32_e64 v120, v164, v174
	v_add_f32_e64 v121, v165, v175
	v_add_f32_e64 v122, v162, v172
	v_add_f32_e64 v123, v163, v173
	v_add_f32_e64 v120, v124, v120
	v_add_f32_e64 v121, v125, v121
	v_pk_add_f32 v[122:123], v[126:127], v[122:123]
	v_pk_add_f32 v[118:119], v[118:119], v[120:121]
	v_pk_add_f32 v[116:117], v[116:117], v[122:123]
	ds_read_b128 v[108:111], v167 offset:41568
	v_pk_mov_b32 v[120:121], v[116:117], v[118:119] op_sel:[1,0]
	v_mov_b32_e32 v117, v119
	v_pk_add_f32 v[116:117], v[120:121], v[116:117]
	s_nop 0
	v_add_f32_e32 v116, v116, v117
	v_add_f32_e32 v171, v171, v116
	s_waitcnt lgkmcnt(2)
	v_mfma_f32_32x32x16_bf16 v[16:31], v[104:107], v[112:115], v[16:31]
	v_max3_f32 v104, v80, v81, v48
	v_max3_f32 v105, v82, v83, v49
	s_nop 0
	v_max3_f32 v104, v104, v50, v51
	v_max3_f32 v105, v105, v86, v87
	s_nop 0
	v_max3_f32 v104, v104, v84, v85
	v_max3_f32 v105, v105, v54, v55
	s_nop 0
	v_max3_f32 v104, v104, v52, v53
	s_waitcnt lgkmcnt(1)
	v_mfma_f32_32x32x16_bf16 v[0:15], v[96:99], v[100:103], v[0:15]
	v_max3_f32 v96, v104, v88, v89
	v_max3_f32 v97, v105, v90, v91
	s_nop 0
	v_max3_f32 v96, v96, v56, v57
	v_max3_f32 v97, v97, v58, v59
	s_nop 0
	v_max3_f32 v96, v96, v92, v93
	v_max3_f32 v97, v97, v94, v95
	s_nop 0
	v_max3_f32 v96, v96, v60, v61
	v_max3_f32 v97, v97, v62, v63
	s_waitcnt lgkmcnt(0)
	v_mfma_f32_32x32x16_bf16 v[16:31], v[108:111], v[100:103], v[16:31]
	v_max_f32_e32 v96, v96, v97
	s_nop 0
	v_mov_b32_e32 v97, v96
	s_nop 1
	v_permlane32_swap_b32_e32 v96, v97
	v_max_f32_e32 v96, v96, v97
	s_nop 0
	v_cmp_lt_f32_e32 vcc, s3, v96
	s_cbranch_vccz .LBB0_396
; #define LAS __attribute__((address_space(3)))
; __device__ __forceinline__ float fast_exp2(float x) { return __builtin_amdgcn_exp2f(x); }
; #define MFMA32(a, b, c) __builtin_amdgcn_mfma_f32_32x32x16_bf16((a), (b), (c), 0, 0, 0)
; template <int DV, int PAR, bool KW = true, bool KL = true, bool VL = true>
; __device__ __forceinline__ void attn_iter_full(AttnState<DV>& S, int t, LAS unsigned char* lds) {
;     ...
;     sn0 = S.negm; sn1 = S.negm;
;     u32x4 pw[4]; float mxa = 0.f, mxb = 0.f, mx = 0.f; f32x16 ssum;
;     constexpr int PD = (DV == 64) ? 3 : 2; bf16x8 fr[PD + 1];
;     ...
; #pragma unroll
;     for (int i = 0; i < PD; ++i) fr[i] = AT_FRAG(i);
;     __builtin_amdgcn_sched_barrier(0);
; #pragma unroll
;     for (int i = 0; i < NS; ++i) {
;         if (i + PD < NS) fr[(i + PD) % (PD + 1)] = AT_FRAG(i + PD);
;         if (i == 3) {
;             if (KW) *(LAS u32x4*)(lds + AT_K0 + PAR * AT_KB + S.kl) = S.kreg;
;             LAS unsigned char* W = lds + AT_V0 + (PAR ^ 1) * AT_VB + S.vl; *(LAS u32x4*)W = S.vreg0; if (DV == 128) *(LAS u32x4*)(W + 64 * 144) = S.vreg1; }
;         if (i == 5) { if (KL) S.kreg = *(const u32x4*)(S.kg + (size_t)(t + 3) * 4096);
;             if (VL) { S.vreg0 = *(const u32x4*)(S.vg + (t + 2) * 64); if (DV == 128) S.vreg1 = *(const u32x4*)(S.vg + (size_t)64 * TK + (t + 2) * 64); } }
;         if (i < 8) { if (i & 1) sn1 = MFMA32(fr[i % (PD + 1)], S.qr[i >> 1], sn1); else sn0 = MFMA32(fr[i % (PD + 1)], S.qr[i >> 1], sn0); }
;         else { const int j = i - 8; S.o[j % NDB] = MFMA32(fr[i % (PD + 1)], __builtin_bit_cast(bf16x8, pw[j / NDB]), S.o[j % NDB]); }
; #pragma unroll
;         for (int u = 0; u < NU; ++u) {
;             if (u * NS / NU != i) continue;
;             if (u < 20) {
;                 const int q = u / 5, r = u % 5;
;                 if (r < 4) { const int e = 8 * q + 2 * r;
;                     if (e < 16) { C0[e] = fast_exp2(C0[e]); C0[e + 1] = fast_exp2(C0[e + 1]); }
;     ...
;     if (__any(mx > 8.0f)) {
;         const float dl = fmaxf(mx, 0.f), alpha = fast_exp2(-dl);
;         S.mrun += dl; S.lsum *= alpha;
; #pragma unroll
;         for (int i = 0; i < 16; ++i) { sn0[i] -= dl; sn1[i] -= dl; S.negm[i] = -S.mrun; }
; #pragma unroll
;         for (int d = 0; d < NDB; ++d)
; #pragma unroll
;             for (int i = 0; i < 16; ++i) S.o[d][i] *= alpha;
;     }
	v_max_f32_e32 v32, v96, v96
	v_max_f32_e32 v33, 0, v32
	v_exp_f32_e64 v34, -v33
	v_add_f32_e32 v170, v170, v33
	v_xor_b32_e32 v32, 0x80000000, v170
	v_sub_f32_e32 v95, v95, v33
	v_mul_f32_e32 v171, v171, v34
	v_sub_f32_e32 v94, v94, v33
	v_sub_f32_e32 v93, v93, v33
	v_sub_f32_e32 v92, v92, v33
	v_sub_f32_e32 v91, v91, v33
	v_sub_f32_e32 v90, v90, v33
	v_sub_f32_e32 v89, v89, v33
	v_sub_f32_e32 v88, v88, v33
	v_sub_f32_e32 v87, v87, v33
	v_sub_f32_e32 v86, v86, v33
	v_sub_f32_e32 v85, v85, v33
	v_sub_f32_e32 v84, v84, v33
	v_sub_f32_e32 v83, v83, v33
	v_sub_f32_e32 v82, v82, v33
	v_sub_f32_e32 v81, v81, v33
	v_sub_f32_e32 v80, v80, v33
	v_sub_f32_e32 v63, v63, v33
	v_sub_f32_e32 v62, v62, v33
	v_sub_f32_e32 v61, v61, v33
	v_sub_f32_e32 v60, v60, v33
	v_sub_f32_e32 v59, v59, v33
	v_sub_f32_e32 v58, v58, v33
	v_sub_f32_e32 v57, v57, v33
	v_sub_f32_e32 v56, v56, v33
	v_sub_f32_e32 v55, v55, v33
	v_sub_f32_e32 v54, v54, v33
	v_sub_f32_e32 v53, v53, v33
	v_sub_f32_e32 v52, v52, v33
	v_sub_f32_e32 v51, v51, v33
	v_sub_f32_e32 v50, v50, v33
	v_sub_f32_e32 v49, v49, v33
	v_sub_f32_e32 v48, v48, v33
	v_pk_mul_f32 v[14:15], v[14:15], v[34:35] op_sel_hi:[1,0]
	v_pk_mul_f32 v[12:13], v[12:13], v[34:35] op_sel_hi:[1,0]
	v_pk_mul_f32 v[10:11], v[10:11], v[34:35] op_sel_hi:[1,0]
	v_pk_mul_f32 v[8:9], v[8:9], v[34:35] op_sel_hi:[1,0]
	v_pk_mul_f32 v[6:7], v[6:7], v[34:35] op_sel_hi:[1,0]
	v_pk_mul_f32 v[4:5], v[4:5], v[34:35] op_sel_hi:[1,0]
	v_pk_mul_f32 v[2:3], v[2:3], v[34:35] op_sel_hi:[1,0]
	v_pk_mul_f32 v[0:1], v[0:1], v[34:35] op_sel_hi:[1,0]
	v_pk_mul_f32 v[30:31], v[30:31], v[34:35] op_sel_hi:[1,0]
	v_pk_mul_f32 v[28:29], v[28:29], v[34:35] op_sel_hi:[1,0]
	v_pk_mul_f32 v[26:27], v[26:27], v[34:35] op_sel_hi:[1,0]
	v_pk_mul_f32 v[24:25], v[24:25], v[34:35] op_sel_hi:[1,0]
	v_pk_mul_f32 v[22:23], v[22:23], v[34:35] op_sel_hi:[1,0]
	v_pk_mul_f32 v[20:21], v[20:21], v[34:35] op_sel_hi:[1,0]
	v_pk_mul_f32 v[18:19], v[18:19], v[34:35] op_sel_hi:[1,0]
	v_pk_mul_f32 v[16:17], v[16:17], v[34:35] op_sel_hi:[1,0]
	v_mov_b32_e32 v33, v32
	v_mov_b32_e32 v34, v32
	v_mov_b32_e32 v35, v32
	v_mov_b32_e32 v36, v32
	v_mov_b32_e32 v37, v32
	v_mov_b32_e32 v38, v32
	v_mov_b32_e32 v39, v32
	v_mov_b32_e32 v40, v32
	v_mov_b32_e32 v41, v32
	v_mov_b32_e32 v42, v32
	v_mov_b32_e32 v43, v32
	v_mov_b32_e32 v44, v32
	v_mov_b32_e32 v45, v32
	v_mov_b32_e32 v46, v32
	v_mov_b32_e32 v47, v32
	v_mov_b32_e32 v64, v32
	v_mov_b32_e32 v65, v32
	v_mov_b32_e32 v66, v32
	v_mov_b32_e32 v67, v32
	v_mov_b32_e32 v68, v32
	v_mov_b32_e32 v69, v32
	v_mov_b32_e32 v70, v32
	v_mov_b32_e32 v71, v32
	v_mov_b32_e32 v72, v32
	v_mov_b32_e32 v73, v32
	v_mov_b32_e32 v74, v32
	v_mov_b32_e32 v75, v32
	v_mov_b32_e32 v76, v32
	v_mov_b32_e32 v77, v32
	v_mov_b32_e32 v78, v32
	v_mov_b32_e32 v79, v32
	s_branch .LBB0_396
.LBB0_402:
	s_cbranch_execz .LBB0_358
	s_branch .LBB0_483
.Lmy_x403:
	v_mov_b64_e32 v[32:33], v[64:65]
	v_mov_b64_e32 v[34:35], v[66:67]
	v_mov_b64_e32 v[36:37], v[68:69]
	v_mov_b64_e32 v[38:39], v[70:71]
	v_mov_b64_e32 v[40:41], v[72:73]
	v_mov_b64_e32 v[42:43], v[74:75]
	v_mov_b64_e32 v[44:45], v[76:77]
	v_mov_b64_e32 v[46:47], v[78:79]
.LBB0_403:
	ds_read_b128 v[64:67], v169 offset:9216
	ds_read_b128 v[112:115], v169 offset:13824
	ds_read_b128 v[116:119], v169 offset:9248
	s_waitcnt lgkmcnt(2)
	v_mfma_f32_32x32x16_bf16 v[96:111], v[64:67], v[140:143], v[32:47]
	ds_read_b128 v[124:127], v169 offset:13856
	v_exp_f32_e32 v122, v80
	v_exp_f32_e32 v123, v81
	v_exp_f32_e32 v80, v82
	v_exp_f32_e32 v81, v83
	s_waitcnt lgkmcnt(2)
	v_mfma_f32_32x32x16_bf16 v[64:79], v[112:115], v[140:143], v[32:47]
	ds_read_b128 v[156:159], v169 offset:9280
	v_exp_f32_e32 v172, v84
	v_exp_f32_e32 v173, v85
	v_exp_f32_e32 v174, v86
	v_exp_f32_e32 v175, v87
	s_waitcnt lgkmcnt(2)
	v_mfma_f32_32x32x16_bf16 v[96:111], v[116:119], v[136:139], v[96:111]
	ds_read_b128 v[82:85], v169 offset:13888
	v_cvt_pk_bf16_f32 v162, v122, v123
	v_cvt_pk_bf16_f32 v163, v80, v81
	v_cvt_pk_bf16_f32 v164, v172, v173
	v_cvt_pk_bf16_f32 v165, v174, v175
	v_exp_f32_e32 v176, v88
	v_exp_f32_e32 v177, v89
	s_waitcnt lgkmcnt(2)
	v_mfma_f32_32x32x16_bf16 v[64:79], v[124:127], v[136:139], v[64:79]
	ds_read_b128 v[86:89], v169 offset:9312
	s_waitcnt vmcnt(1)
	ds_write_b128 v168, v[144:147]
	s_waitcnt vmcnt(0)
	ds_write_b128 v168, v[148:151] offset:36864
	v_exp_f32_e32 v148, v90
	v_exp_f32_e32 v149, v91
	s_waitcnt lgkmcnt(4)
	v_mfma_f32_32x32x16_bf16 v[96:111], v[156:159], v[132:135], v[96:111]
	ds_read_b128 v[124:127], v169 offset:13920
	v_exp_f32_e32 v150, v92
	v_exp_f32_e32 v151, v93
	v_exp_f32_e32 v94, v94
	v_exp_f32_e32 v95, v95
	s_mov_b32 s2, 0x86000
	v_add_co_u32_e32 v112, vcc, s2, v154
	s_movk_i32 s2, 0x2000
	s_nop 0
	v_addc_co_u32_e32 v113, vcc, 0, v155, vcc
	v_add_co_u32_e32 v120, vcc, s2, v152
	ds_read_b128 v[90:93], v167 offset:18432
	s_nop 0
	v_addc_co_u32_e32 v121, vcc, 0, v153, vcc
	global_load_dwordx4 v[112:115], v[112:113], off
	s_nop 0
	global_load_dwordx4 v[116:119], v[120:121], off offset:256
	s_waitcnt lgkmcnt(5)
	v_mfma_f32_32x32x16_bf16 v[64:79], v[82:85], v[132:135], v[64:79]
	v_cvt_pk_bf16_f32 v82, v176, v177
	v_exp_f32_e32 v152, v48
	v_exp_f32_e32 v153, v49
	v_cvt_pk_bf16_f32 v83, v148, v149
	v_cvt_pk_bf16_f32 v84, v150, v151
	v_cvt_pk_bf16_f32 v85, v94, v95
	s_waitcnt lgkmcnt(4)
	v_mfma_f32_32x32x16_bf16 v[96:111], v[86:89], v[128:131], v[96:111]
	ds_read_b128 v[144:147], v167 offset:23040
	v_exp_f32_e32 v154, v50
	v_exp_f32_e32 v155, v51
	s_waitcnt lgkmcnt(2)
	v_mfma_f32_32x32x16_bf16 v[64:79], v[124:127], v[128:131], v[64:79]
	ds_read_b128 v[48:51], v167 offset:18464
	v_exp_f32_e32 v126, v54
	v_exp_f32_e32 v124, v52
	v_exp_f32_e32 v125, v53
	v_exp_f32_e32 v127, v55
	s_waitcnt lgkmcnt(2)
; template <int DV, int PAR, bool KW = true, bool KL = true, bool VL = true>
; __device__ __forceinline__ void attn_iter_full(AttnState<DV>& S, int t, LAS unsigned char* lds) {
;     ...
;         if (i < 8) { if (i & 1) sn1 = MFMA32(fr[i % (PD + 1)], S.qr[i >> 1], sn1); else sn0 = MFMA32(fr[i % (PD + 1)], S.qr[i >> 1], sn0); }
;         else { const int j = i - 8; S.o[j % NDB] = MFMA32(fr[i % (PD + 1)], __builtin_bit_cast(bf16x8, pw[j / NDB]), S.o[j % NDB]); }
; #pragma unroll
;         for (int u = 0; u < NU; ++u) {
;             if (u * NS / NU != i) continue;
;             if (u < 20) {
;                 const int q = u / 5, r = u % 5;
;                 if (r < 4) { const int e = 8 * q + 2 * r;
;                     if (e < 16) { C0[e] = fast_exp2(C0[e]); C0[e + 1] = fast_exp2(C0[e + 1]); }
;                     else { C1[e - 16] = fast_exp2(C1[e - 16]); C1[e - 15] = fast_exp2(C1[e - 15]); } }
;                 else { if (q < 2) { const int b0 = 8 * q; pw[q].x = pk2(C0[b0], C0[b0 + 1]); pw[q].y = pk2(C0[b0 + 2], C0[b0 + 3]); pw[q].z = pk2(C0[b0 + 4], C0[b0 + 5]); pw[q].w = pk2(C0[b0 + 6], C0[b0 + 7]); }
;                        else { const int b0 = 8 * (q - 2); pw[q].x = pk2(C1[b0], C1[b0 + 1]); pw[q].y = pk2(C1[b0 + 2], C1[b0 + 3]); pw[q].z = pk2(C1[b0 + 4], C1[b0 + 5]); pw[q].w = pk2(C1[b0 + 6], C1[b0 + 7]); } }
;             } else if (u == 20) { ssum = C0 + C1; }
;             else if (u == 21) { const f32x4 a = (f32x4){ssum[0], ssum[1], ssum[2], ssum[3]} + (f32x4){ssum[4], ssum[5], ssum[6], ssum[7]} + (f32x4){ssum[8], ssum[9], ssum[10], ssum[11]} + (f32x4){ssum[12], ssum[13], ssum[14], ssum[15]};
;                 S.lsum += (a[0] + a[1]) + (a[2] + a[3]); }
;             else if (u == 22) { mxa = max3f(sn0[0], sn0[1], sn1[0]); mxb = max3f(sn0[2], sn0[3], sn1[1]); mxa = max3f(mxa, sn1[2], sn1[3]); }
;             else if (u < 26) { const int r = 4 * (u - 22); mxa = max3f(mxa, sn0[r], sn0[r + 1]); mxb = max3f(mxb, sn0[r + 2], sn0[r + 3]); mxa = max3f(mxa, sn1[r], sn1[r + 1]); mxb = max3f(mxb, sn1[r + 2], sn1[r + 3]); }
;             else { const float m = max2f(mxa, mxb); auto rr = __builtin_amdgcn_permlane32_swap(__float_as_uint(m), __float_as_uint(m), false, false); mx = max2f(__uint_as_float(rr[0]), __uint_as_float(rr[1])); }
;         }
;         __builtin_amdgcn_sched_barrier(0);
;     }
;     ...
;     if (__any(mx > 8.0f)) {
	v_mfma_f32_32x32x16_bf16 v[0:15], v[90:93], v[162:165], v[0:15]
	ds_read_b128 v[52:55], v167 offset:23072
	v_cvt_pk_bf16_f32 v86, v152, v153
	v_cvt_pk_bf16_f32 v87, v154, v155
	v_cvt_pk_bf16_f32 v88, v124, v125
	v_cvt_pk_bf16_f32 v89, v126, v127
	v_exp_f32_e32 v156, v56
	v_exp_f32_e32 v157, v57
	s_waitcnt lgkmcnt(2)
	v_mfma_f32_32x32x16_bf16 v[16:31], v[144:147], v[162:165], v[16:31]
	ds_read_b128 v[90:93], v167 offset:18496
	v_exp_f32_e32 v144, v58
	v_exp_f32_e32 v145, v59
	s_waitcnt lgkmcnt(2)
	v_mfma_f32_32x32x16_bf16 v[0:15], v[48:51], v[82:85], v[0:15]
	ds_read_b128 v[56:59], v167 offset:23104
	v_exp_f32_e32 v60, v60
	v_exp_f32_e32 v61, v61
	v_exp_f32_e32 v62, v62
	v_exp_f32_e32 v63, v63
	s_waitcnt lgkmcnt(2)
	v_mfma_f32_32x32x16_bf16 v[16:31], v[52:55], v[82:85], v[16:31]
	ds_read_b128 v[48:51], v167 offset:18528
	v_add_f32_e64 v126, v126, v174
	v_add_f32_e64 v127, v127, v175
	v_cvt_pk_bf16_f32 v52, v156, v157
	v_cvt_pk_bf16_f32 v53, v144, v145
	v_cvt_pk_bf16_f32 v54, v60, v61
	v_cvt_pk_bf16_f32 v55, v62, v63
	v_pk_add_f32 v[82:83], v[60:61], v[150:151]
	v_pk_add_f32 v[84:85], v[62:63], v[94:95]
	v_pk_add_f32 v[94:95], v[144:145], v[148:149]
	v_pk_add_f32 v[144:145], v[156:157], v[176:177]
	v_pk_add_f32 v[124:125], v[124:125], v[172:173]
	v_pk_add_f32 v[122:123], v[152:153], v[122:123]
	v_pk_add_f32 v[80:81], v[154:155], v[80:81]
	s_waitcnt lgkmcnt(2)
	v_mfma_f32_32x32x16_bf16 v[0:15], v[90:93], v[86:89], v[0:15]
	v_add_f32_e64 v80, v80, v126
	v_add_f32_e64 v81, v81, v127
	v_add_f32_e64 v90, v122, v124
	v_add_f32_e64 v91, v123, v125
	v_add_f32_e64 v80, v94, v80
	v_add_f32_e64 v81, v95, v81
	v_pk_add_f32 v[90:91], v[144:145], v[90:91]
	v_pk_add_f32 v[80:81], v[84:85], v[80:81]
	v_pk_add_f32 v[82:83], v[82:83], v[90:91]
	ds_read_b128 v[60:63], v167 offset:23136
	v_pk_mov_b32 v[84:85], v[82:83], v[80:81] op_sel:[1,0]
	v_mov_b32_e32 v83, v81
	v_pk_add_f32 v[80:81], v[84:85], v[82:83]
	s_nop 0
	v_add_f32_e32 v80, v80, v81
	v_add_f32_e32 v126, v171, v80
	s_waitcnt lgkmcnt(2)
	v_mfma_f32_32x32x16_bf16 v[16:31], v[56:59], v[86:89], v[16:31]
	v_max3_f32 v56, v96, v97, v64
	v_max3_f32 v57, v98, v99, v65
	s_nop 0
	v_max3_f32 v56, v56, v66, v67
	v_max3_f32 v57, v57, v102, v103
	s_nop 0
	v_max3_f32 v56, v56, v100, v101
	v_max3_f32 v57, v57, v70, v71
	s_nop 0
	v_max3_f32 v56, v56, v68, v69
	s_waitcnt lgkmcnt(1)
	v_mfma_f32_32x32x16_bf16 v[0:15], v[48:51], v[52:55], v[0:15]
	v_max3_f32 v48, v56, v104, v105
	v_max3_f32 v49, v57, v106, v107
	s_nop 0
	v_max3_f32 v48, v48, v72, v73
	v_max3_f32 v49, v49, v74, v75
	s_nop 0
	v_max3_f32 v48, v48, v108, v109
	v_max3_f32 v49, v49, v110, v111
	s_nop 0
	v_max3_f32 v48, v48, v76, v77
	v_max3_f32 v49, v49, v78, v79
	s_waitcnt lgkmcnt(0)
	v_mfma_f32_32x32x16_bf16 v[16:31], v[60:63], v[52:55], v[16:31]
	v_max_f32_e32 v48, v48, v49
	s_nop 0
	v_mov_b32_e32 v49, v48
	s_nop 1
	v_permlane32_swap_b32_e32 v48, v49
	v_max_f32_e32 v48, v48, v49
	s_nop 0
	v_cmp_lt_f32_e32 vcc, s3, v48
	s_cbranch_vccz .LBB0_405
	v_max_f32_e32 v32, v48, v48
	v_max_f32_e32 v34, 0, v32
	v_exp_f32_e64 v36, -v34
	v_add_f32_e32 v170, v170, v34
	v_xor_b32_e32 v32, 0x80000000, v170
	v_pk_add_f32 v[96:97], v[96:97], v[34:35] op_sel_hi:[1,0] neg_lo:[0,1] neg_hi:[0,1]
	v_mul_f32_e32 v126, v126, v36
	v_pk_add_f32 v[64:65], v[64:65], v[34:35] op_sel_hi:[1,0] neg_lo:[0,1] neg_hi:[0,1]
	v_pk_add_f32 v[98:99], v[98:99], v[34:35] op_sel_hi:[1,0] neg_lo:[0,1] neg_hi:[0,1]
	v_pk_add_f32 v[66:67], v[66:67], v[34:35] op_sel_hi:[1,0] neg_lo:[0,1] neg_hi:[0,1]
	v_pk_add_f32 v[100:101], v[100:101], v[34:35] op_sel_hi:[1,0] neg_lo:[0,1] neg_hi:[0,1]
	v_pk_add_f32 v[68:69], v[68:69], v[34:35] op_sel_hi:[1,0] neg_lo:[0,1] neg_hi:[0,1]
	v_pk_add_f32 v[102:103], v[102:103], v[34:35] op_sel_hi:[1,0] neg_lo:[0,1] neg_hi:[0,1]
	v_pk_add_f32 v[70:71], v[70:71], v[34:35] op_sel_hi:[1,0] neg_lo:[0,1] neg_hi:[0,1]
	v_pk_add_f32 v[104:105], v[104:105], v[34:35] op_sel_hi:[1,0] neg_lo:[0,1] neg_hi:[0,1]
	v_pk_add_f32 v[72:73], v[72:73], v[34:35] op_sel_hi:[1,0] neg_lo:[0,1] neg_hi:[0,1]
	v_pk_add_f32 v[106:107], v[106:107], v[34:35] op_sel_hi:[1,0] neg_lo:[0,1] neg_hi:[0,1]
	v_pk_add_f32 v[74:75], v[74:75], v[34:35] op_sel_hi:[1,0] neg_lo:[0,1] neg_hi:[0,1]
	v_pk_add_f32 v[108:109], v[108:109], v[34:35] op_sel_hi:[1,0] neg_lo:[0,1] neg_hi:[0,1]
	v_pk_add_f32 v[76:77], v[76:77], v[34:35] op_sel_hi:[1,0] neg_lo:[0,1] neg_hi:[0,1]
	v_pk_add_f32 v[110:111], v[110:111], v[34:35] op_sel_hi:[1,0] neg_lo:[0,1] neg_hi:[0,1]
	v_pk_add_f32 v[78:79], v[78:79], v[34:35] op_sel_hi:[1,0] neg_lo:[0,1] neg_hi:[0,1]
	v_pk_mul_f32 v[14:15], v[14:15], v[36:37] op_sel_hi:[1,0]
	v_pk_mul_f32 v[12:13], v[12:13], v[36:37] op_sel_hi:[1,0]
	v_pk_mul_f32 v[10:11], v[10:11], v[36:37] op_sel_hi:[1,0]
	v_pk_mul_f32 v[8:9], v[8:9], v[36:37] op_sel_hi:[1,0]
	v_pk_mul_f32 v[6:7], v[6:7], v[36:37] op_sel_hi:[1,0]
	v_pk_mul_f32 v[4:5], v[4:5], v[36:37] op_sel_hi:[1,0]
	v_pk_mul_f32 v[2:3], v[2:3], v[36:37] op_sel_hi:[1,0]
	v_pk_mul_f32 v[0:1], v[0:1], v[36:37] op_sel_hi:[1,0]
	v_pk_mul_f32 v[30:31], v[30:31], v[36:37] op_sel_hi:[1,0]
	v_pk_mul_f32 v[28:29], v[28:29], v[36:37] op_sel_hi:[1,0]
	v_pk_mul_f32 v[26:27], v[26:27], v[36:37] op_sel_hi:[1,0]
	v_pk_mul_f32 v[24:25], v[24:25], v[36:37] op_sel_hi:[1,0]
	v_pk_mul_f32 v[22:23], v[22:23], v[36:37] op_sel_hi:[1,0]
	v_pk_mul_f32 v[20:21], v[20:21], v[36:37] op_sel_hi:[1,0]
	v_pk_mul_f32 v[18:19], v[18:19], v[36:37] op_sel_hi:[1,0]
	v_pk_mul_f32 v[16:17], v[16:17], v[36:37] op_sel_hi:[1,0]
	v_mov_b32_e32 v33, v32
	v_mov_b32_e32 v34, v32
	v_mov_b32_e32 v35, v32
	v_mov_b32_e32 v36, v32
	v_mov_b32_e32 v37, v32
	v_mov_b32_e32 v38, v32
	v_mov_b32_e32 v39, v32
	v_mov_b32_e32 v40, v32
	v_mov_b32_e32 v41, v32
	v_mov_b32_e32 v42, v32
	v_mov_b32_e32 v43, v32
	v_mov_b32_e32 v44, v32
	v_mov_b32_e32 v45, v32
	v_mov_b32_e32 v46, v32
	v_mov_b32_e32 v47, v32

; template <int DV, int PAR, bool KW = true, bool KL = true, bool VL = true>
; __device__ __forceinline__ void attn_iter_full(AttnState<DV>& S, int t, LAS unsigned char* lds) {
;     ...
;     f32x16& C0 = PAR ? S.sd0 : S.sc0; f32x16& C1 = PAR ? S.sd1 : S.sc1; f32x16& sn0 = PAR ? S.sc0 : S.sd0; f32x16& sn1 = PAR ? S.sc1 : S.sd1;
;     sn0 = S.negm; sn1 = S.negm;
;     u32x4 pw[4]; float mxa = 0.f, mxb = 0.f, mx = 0.f; f32x16 ssum;
;     constexpr int PD = (DV == 64) ? 3 : 2; bf16x8 fr[PD + 1];
;     ...
; #pragma unroll
;     for (int i = 0; i < PD; ++i) fr[i] = AT_FRAG(i);
;     __builtin_amdgcn_sched_barrier(0);
; #pragma unroll
;     for (int i = 0; i < NS; ++i) {
;         if (i + PD < NS) fr[(i + PD) % (PD + 1)] = AT_FRAG(i + PD);
;         if (i == 3) {
;             if (KW) *(LAS u32x4*)(lds + AT_K0 + PAR * AT_KB + S.kl) = S.kreg;
;             LAS unsigned char* W = lds + AT_V0 + (PAR ^ 1) * AT_VB + S.vl; *(LAS u32x4*)W = S.vreg0; if (DV == 128) *(LAS u32x4*)(W + 64 * 144) = S.vreg1; }
;         if (i == 5) { if (KL) S.kreg = *(const u32x4*)(S.kg + (size_t)(t + 3) * 4096);
;             if (VL) { S.vreg0 = *(const u32x4*)(S.vg + (t + 2) * 64); if (DV == 128) S.vreg1 = *(const u32x4*)(S.vg + (size_t)64 * TK + (t + 2) * 64); } }
;         if (i < 8) { if (i & 1) sn1 = MFMA32(fr[i % (PD + 1)], S.qr[i >> 1], sn1); else sn0 = MFMA32(fr[i % (PD + 1)], S.qr[i >> 1], sn0); }
;         else { const int j = i - 8; S.o[j % NDB] = MFMA32(fr[i % (PD + 1)], __builtin_bit_cast(bf16x8, pw[j / NDB]), S.o[j % NDB]); }
; #pragma unroll
;         for (int u = 0; u < NU; ++u) {
;             if (u * NS / NU != i) continue;
;             if (u < 20) {
;                 const int q = u / 5, r = u % 5;
;                 if (r < 4) { const int e = 8 * q + 2 * r;
;                     if (e < 16) { C0[e] = fast_exp2(C0[e]); C0[e + 1] = fast_exp2(C0[e + 1]); }
;                     else { C1[e - 16] = fast_exp2(C1[e - 16]); C1[e - 15] = fast_exp2(C1[e - 15]); } }
;                 else { if (q < 2) { const int b0 = 8 * q; pw[q].x = pk2(C0[b0], C0[b0 + 1]); pw[q].y = pk2(C0[b0 + 2], C0[b0 + 3]); pw[q].z = pk2(C0[b0 + 4], C0[b0 + 5]); pw[q].w = pk2(C0[b0 + 6], C0[b0 + 7]); }
;                        else { const int b0 = 8 * (q - 2); pw[q].x = pk2(C1[b0], C1[b0 + 1]); pw[q].y = pk2(C1[b0 + 2], C1[b0 + 3]); pw[q].z = pk2(C1[b0 + 4], C1[b0 + 5]); pw[q].w = pk2(C1[b0 + 6], C1[b0 + 7]); } }
.LBB0_416:
.LBB0_417:
	s_barrier
	ds_read_b128 v[80:83], v231
	ds_read_b128 v[242:245], v231 offset:4608
	s_waitcnt lgkmcnt(1)
	v_mfma_f32_32x32x16_bf16 v[112:127], v[80:83], v[174:177], v[96:111]
	ds_read_b128 v[246:249], v231 offset:32
	v_exp_f32_e32 v216, v144
	v_exp_f32_e32 v217, v145
	v_exp_f32_e32 v144, v146
	v_exp_f32_e32 v145, v147
	s_waitcnt lgkmcnt(1)
	v_mfma_f32_32x32x16_bf16 v[80:95], v[242:245], v[174:177], v[96:111]
	ds_read_b128 v[190:193], v231 offset:4640
	v_exp_f32_e32 v146, v148
	v_exp_f32_e32 v147, v149
	s_waitcnt lgkmcnt(1)
	v_mfma_f32_32x32x16_bf16 v[112:127], v[246:249], v[170:173], v[112:127]
	ds_read_b128 v[242:245], v231 offset:64
	v_exp_f32_e32 v148, v150
	v_exp_f32_e32 v149, v151
	s_waitcnt lgkmcnt(1)
	v_mfma_f32_32x32x16_bf16 v[80:95], v[190:193], v[170:173], v[80:95]
	ds_read_b128 v[246:249], v231 offset:4672
	s_waitcnt vmcnt(2)
	ds_write_b128 v232, v[178:181] offset:9216
	s_waitcnt vmcnt(1)
	ds_write_b128 v232, v[182:185] offset:18432
	s_waitcnt vmcnt(0)
	ds_write_b128 v232, v[186:189] offset:27648
	v_cvt_pk_bf16_f32 v196, v216, v217
	v_cvt_pk_bf16_f32 v197, v144, v145
	v_cvt_pk_bf16_f32 v198, v146, v147
	v_cvt_pk_bf16_f32 v199, v148, v149
	s_waitcnt lgkmcnt(4)
	v_mfma_f32_32x32x16_bf16 v[112:127], v[242:245], v[166:169], v[112:127]
	ds_read_b128 v[190:193], v231 offset:96
	v_exp_f32_e32 v150, v152
	v_exp_f32_e32 v151, v153
	s_mov_b32 s15, 0x10e08000
	v_add_co_u32_e32 v152, vcc, s15, v210
	ds_read_b128 v[242:245], v231 offset:4704
	s_nop 0
	v_addc_co_u32_e32 v153, vcc, 0, v211, vcc
	global_load_dwordx4 v[178:181], v[152:153], off
	global_load_dwordx4 v[182:185], v[212:213], off offset:384
	global_load_dwordx4 v[186:189], v[214:215], off offset:384
	s_waitcnt lgkmcnt(5)
	v_mfma_f32_32x32x16_bf16 v[80:95], v[246:249], v[166:169], v[80:95]
	v_exp_f32_e32 v214, v154
	v_exp_f32_e32 v215, v155
	s_waitcnt lgkmcnt(1)
	v_mfma_f32_32x32x16_bf16 v[112:127], v[190:193], v[162:165], v[112:127]
	ds_read_b128 v[152:155], v230 offset:36864
	v_exp_f32_e32 v236, v156
	v_exp_f32_e32 v237, v157
	s_waitcnt lgkmcnt(1)
	v_mfma_f32_32x32x16_bf16 v[80:95], v[242:245], v[162:165], v[80:95]
	ds_read_b128 v[190:193], v230 offset:41472
	v_exp_f32_e32 v242, v158
	v_exp_f32_e32 v243, v159
	s_waitcnt lgkmcnt(1)
	v_mfma_f32_32x32x16_bf16 v[48:63], v[152:155], v[196:199], v[48:63]
	ds_read_b128 v[156:159], v230 offset:46080
	v_cvt_pk_bf16_f32 v152, v150, v151
	v_cvt_pk_bf16_f32 v153, v214, v215
	v_cvt_pk_bf16_f32 v154, v236, v237
	v_cvt_pk_bf16_f32 v155, v242, v243
	v_exp_f32_e32 v244, v128
	v_exp_f32_e32 v245, v129
	s_waitcnt lgkmcnt(1)
	v_mfma_f32_32x32x16_bf16 v[32:47], v[190:193], v[196:199], v[32:47]
	ds_read_b128 v[210:213], v230 offset:50688
	v_exp_f32_e32 v246, v130
	v_exp_f32_e32 v247, v131
	s_waitcnt lgkmcnt(1)
	v_mfma_f32_32x32x16_bf16 v[16:31], v[156:159], v[196:199], v[16:31]
	ds_read_b128 v[128:131], v230 offset:36896
	v_exp_f32_e32 v248, v132
	v_exp_f32_e32 v249, v133
	s_waitcnt lgkmcnt(1)
	v_mfma_f32_32x32x16_bf16 v[0:15], v[210:213], v[196:199], v[0:15]
	ds_read_b128 v[156:159], v230 offset:41504
	v_exp_f32_e32 v196, v134
	v_exp_f32_e32 v197, v135
	s_waitcnt lgkmcnt(1)
	v_mfma_f32_32x32x16_bf16 v[48:63], v[128:131], v[152:155], v[48:63]
	ds_read_b128 v[132:135], v230 offset:46112
	v_cvt_pk_bf16_f32 v128, v244, v245
	v_cvt_pk_bf16_f32 v129, v246, v247
	v_cvt_pk_bf16_f32 v130, v248, v249
	v_cvt_pk_bf16_f32 v131, v196, v197
	s_waitcnt lgkmcnt(1)
	v_mfma_f32_32x32x16_bf16 v[32:47], v[156:159], v[152:155], v[32:47]
	ds_read_b128 v[190:193], v230 offset:50720
	v_exp_f32_e32 v198, v136
	v_exp_f32_e32 v199, v137
	s_waitcnt lgkmcnt(1)
	v_mfma_f32_32x32x16_bf16 v[16:31], v[132:135], v[152:155], v[16:31]
	ds_read_b128 v[156:159], v230 offset:36928
	v_exp_f32_e32 v210, v138
	v_exp_f32_e32 v211, v139
	s_waitcnt lgkmcnt(1)
	v_mfma_f32_32x32x16_bf16 v[0:15], v[190:193], v[152:155], v[0:15]
	ds_read_b128 v[132:135], v230 offset:41536
	v_exp_f32_e32 v190, v140
	v_exp_f32_e32 v191, v141
	s_waitcnt lgkmcnt(1)
	v_mfma_f32_32x32x16_bf16 v[48:63], v[156:159], v[128:131], v[48:63]
	ds_read_b128 v[136:139], v230 offset:46144
	v_exp_f32_e32 v156, v142
	v_exp_f32_e32 v157, v143
	v_cvt_pk_bf16_f32 v140, v198, v199
	v_cvt_pk_bf16_f32 v141, v210, v211
	v_cvt_pk_bf16_f32 v142, v190, v191
	v_cvt_pk_bf16_f32 v143, v156, v157
	s_waitcnt lgkmcnt(1)
	v_mfma_f32_32x32x16_bf16 v[32:47], v[132:135], v[128:131], v[32:47]
	ds_read_b128 v[152:155], v230 offset:50752
	v_add_f32_e64 v158, v190, v236
	v_add_f32_e64 v159, v191, v237
	v_add_f32_e64 v156, v156, v242
	v_add_f32_e64 v157, v157, v243
	v_pk_add_f32 v[190:191], v[210:211], v[214:215]
	v_pk_add_f32 v[150:151], v[198:199], v[150:151]
	v_pk_add_f32 v[146:147], v[248:249], v[146:147]
	v_pk_add_f32 v[192:193], v[244:245], v[216:217]
	v_pk_add_f32 v[148:149], v[196:197], v[148:149]
	v_pk_add_f32 v[144:145], v[246:247], v[144:145]
	s_waitcnt lgkmcnt(1)
	v_mfma_f32_32x32x16_bf16 v[16:31], v[136:139], v[128:131], v[16:31]
	v_add_f32_e64 v136, v144, v148
	v_add_f32_e64 v137, v145, v149
	v_add_f32_e64 v138, v192, v146
	v_add_f32_e64 v139, v193, v147
	v_add_f32_e64 v136, v190, v136
	v_add_f32_e64 v137, v191, v137
	v_pk_add_f32 v[138:139], v[150:151], v[138:139]
	v_pk_add_f32 v[136:137], v[156:157], v[136:137]
	v_pk_add_f32 v[138:139], v[158:159], v[138:139]
	ds_read_b128 v[132:135], v230 offset:36960
	v_pk_mov_b32 v[144:145], v[138:139], v[136:137] op_sel:[1,0]
	v_mov_b32_e32 v139, v137
	v_pk_add_f32 v[136:137], v[144:145], v[138:139]
	s_nop 0
	v_add_f32_e32 v136, v136, v137
	v_add_f32_e32 v216, v234, v136
	s_waitcnt lgkmcnt(1)
	v_mfma_f32_32x32x16_bf16 v[0:15], v[152:155], v[128:131], v[0:15]
	ds_read_b128 v[136:139], v230 offset:41568
	v_max3_f32 v128, v112, v113, v80
	v_max3_f32 v144, v114, v115, v81
	s_nop 0
	v_max3_f32 v145, v128, v82, v83
	s_waitcnt lgkmcnt(1)
	v_mfma_f32_32x32x16_bf16 v[48:63], v[132:135], v[140:143], v[48:63]
	ds_read_b128 v[128:131], v230 offset:46176
	v_max3_f32 v132, v145, v116, v117
	v_max3_f32 v133, v144, v118, v119
	s_nop 0
	v_max3_f32 v144, v132, v84, v85
	v_max3_f32 v145, v133, v86, v87
	s_waitcnt lgkmcnt(1)
	v_mfma_f32_32x32x16_bf16 v[32:47], v[136:139], v[140:143], v[32:47]
	ds_read_b128 v[132:135], v230 offset:50784
	v_max3_f32 v136, v144, v120, v121
	v_max3_f32 v137, v145, v122, v123
	s_nop 0
	v_max3_f32 v136, v136, v88, v89
	v_max3_f32 v137, v137, v90, v91
	s_waitcnt lgkmcnt(1)
	v_mfma_f32_32x32x16_bf16 v[16:31], v[128:131], v[140:143], v[16:31]
	v_max3_f32 v128, v136, v124, v125
	v_max3_f32 v129, v137, v126, v127
	s_nop 0
	v_max3_f32 v128, v128, v92, v93
	v_max3_f32 v129, v129, v94, v95
	s_waitcnt lgkmcnt(0)
	v_mfma_f32_32x32x16_bf16 v[0:15], v[132:135], v[140:143], v[0:15]
	v_max_f32_e32 v128, v128, v129
	s_nop 0
	v_mov_b32_e32 v129, v128
	s_nop 1
	v_permlane32_swap_b32_e32 v128, v129
	v_max_f32_e32 v128, v128, v129
	s_nop 0
	v_cmp_lt_f32_e32 vcc, s3, v128
	s_cbranch_vccz .LBB0_413
; #define LAS __attribute__((address_space(3)))
; __device__ __forceinline__ float fast_exp2(float x) { return __builtin_amdgcn_exp2f(x); }
; #define MFMA32(a, b, c) __builtin_amdgcn_mfma_f32_32x32x16_bf16((a), (b), (c), 0, 0, 0)
; template <int DV, int PAR, bool KW = true, bool KL = true, bool VL = true>
; __device__ __forceinline__ void attn_iter_full(AttnState<DV>& S, int t, LAS unsigned char* lds) {
;     ...
;     sn0 = S.negm; sn1 = S.negm;
;     u32x4 pw[4]; float mxa = 0.f, mxb = 0.f, mx = 0.f; f32x16 ssum;
;     constexpr int PD = (DV == 64) ? 3 : 2; bf16x8 fr[PD + 1];
;     ...
; #pragma unroll
;     for (int i = 0; i < PD; ++i) fr[i] = AT_FRAG(i);
;     __builtin_amdgcn_sched_barrier(0);
; #pragma unroll
;     for (int i = 0; i < NS; ++i) {
;         if (i + PD < NS) fr[(i + PD) % (PD + 1)] = AT_FRAG(i + PD);
;         if (i == 3) {
;             if (KW) *(LAS u32x4*)(lds + AT_K0 + PAR * AT_KB + S.kl) = S.kreg;
;             LAS unsigned char* W = lds + AT_V0 + (PAR ^ 1) * AT_VB + S.vl; *(LAS u32x4*)W = S.vreg0; if (DV == 128) *(LAS u32x4*)(W + 64 * 144) = S.vreg1; }
;         if (i == 5) { if (KL) S.kreg = *(const u32x4*)(S.kg + (size_t)(t + 3) * 4096);
;             if (VL) { S.vreg0 = *(const u32x4*)(S.vg + (t + 2) * 64); if (DV == 128) S.vreg1 = *(const u32x4*)(S.vg + (size_t)64 * TK + (t + 2) * 64); } }
;         if (i < 8) { if (i & 1) sn1 = MFMA32(fr[i % (PD + 1)], S.qr[i >> 1], sn1); else sn0 = MFMA32(fr[i % (PD + 1)], S.qr[i >> 1], sn0); }
;         else { const int j = i - 8; S.o[j % NDB] = MFMA32(fr[i % (PD + 1)], __builtin_bit_cast(bf16x8, pw[j / NDB]), S.o[j % NDB]); }
; #pragma unroll
;         for (int u = 0; u < NU; ++u) {
;             if (u * NS / NU != i) continue;
;             if (u < 20) {
;                 const int q = u / 5, r = u % 5;
;                 if (r < 4) { const int e = 8 * q + 2 * r;
;                     if (e < 16) { C0[e] = fast_exp2(C0[e]); C0[e + 1] = fast_exp2(C0[e + 1]); }
;     ...
;     if (__any(mx > 8.0f)) {
;         const float dl = fmaxf(mx, 0.f), alpha = fast_exp2(-dl);
;         S.mrun += dl; S.lsum *= alpha;
; #pragma unroll
;         for (int i = 0; i < 16; ++i) { sn0[i] -= dl; sn1[i] -= dl; S.negm[i] = -S.mrun; }
; #pragma unroll
;         for (int d = 0; d < NDB; ++d)
; #pragma unroll
;             for (int i = 0; i < 16; ++i) S.o[d][i] *= alpha;
;     }
	v_max_f32_e32 v64, v128, v128
	v_max_f32_e32 v65, 0, v64
	v_exp_f32_e64 v66, -v65
	v_add_f32_e32 v233, v233, v65
	v_xor_b32_e32 v64, 0x80000000, v233
	v_sub_f32_e32 v127, v127, v65
	v_mul_f32_e32 v216, v216, v66
	v_sub_f32_e32 v126, v126, v65
	v_sub_f32_e32 v125, v125, v65
	v_sub_f32_e32 v124, v124, v65
	v_sub_f32_e32 v123, v123, v65
	v_sub_f32_e32 v122, v122, v65
	v_sub_f32_e32 v121, v121, v65
	v_sub_f32_e32 v120, v120, v65
	v_sub_f32_e32 v119, v119, v65
	v_sub_f32_e32 v118, v118, v65
	v_sub_f32_e32 v117, v117, v65
	v_sub_f32_e32 v116, v116, v65
	v_sub_f32_e32 v115, v115, v65
	v_sub_f32_e32 v114, v114, v65
	v_sub_f32_e32 v113, v113, v65
	v_sub_f32_e32 v112, v112, v65
	v_sub_f32_e32 v95, v95, v65
	v_sub_f32_e32 v94, v94, v65
	v_sub_f32_e32 v93, v93, v65
	v_sub_f32_e32 v92, v92, v65
	v_sub_f32_e32 v91, v91, v65
	v_sub_f32_e32 v90, v90, v65
	v_sub_f32_e32 v89, v89, v65
	v_sub_f32_e32 v88, v88, v65
	v_sub_f32_e32 v87, v87, v65
	v_sub_f32_e32 v86, v86, v65
	v_sub_f32_e32 v85, v85, v65
	v_sub_f32_e32 v84, v84, v65
	v_sub_f32_e32 v83, v83, v65
	v_sub_f32_e32 v82, v82, v65
	v_sub_f32_e32 v81, v81, v65
	v_sub_f32_e32 v80, v80, v65
	v_pk_mul_f32 v[62:63], v[62:63], v[66:67] op_sel_hi:[1,0]
	v_pk_mul_f32 v[60:61], v[60:61], v[66:67] op_sel_hi:[1,0]
	v_pk_mul_f32 v[58:59], v[58:59], v[66:67] op_sel_hi:[1,0]
	v_pk_mul_f32 v[56:57], v[56:57], v[66:67] op_sel_hi:[1,0]
	v_pk_mul_f32 v[54:55], v[54:55], v[66:67] op_sel_hi:[1,0]
	v_pk_mul_f32 v[52:53], v[52:53], v[66:67] op_sel_hi:[1,0]
	v_pk_mul_f32 v[50:51], v[50:51], v[66:67] op_sel_hi:[1,0]
	v_pk_mul_f32 v[48:49], v[48:49], v[66:67] op_sel_hi:[1,0]
	v_pk_mul_f32 v[46:47], v[46:47], v[66:67] op_sel_hi:[1,0]
	v_pk_mul_f32 v[44:45], v[44:45], v[66:67] op_sel_hi:[1,0]
	v_pk_mul_f32 v[42:43], v[42:43], v[66:67] op_sel_hi:[1,0]
	v_pk_mul_f32 v[40:41], v[40:41], v[66:67] op_sel_hi:[1,0]
	v_pk_mul_f32 v[38:39], v[38:39], v[66:67] op_sel_hi:[1,0]
	v_pk_mul_f32 v[36:37], v[36:37], v[66:67] op_sel_hi:[1,0]
	v_pk_mul_f32 v[34:35], v[34:35], v[66:67] op_sel_hi:[1,0]
	v_pk_mul_f32 v[32:33], v[32:33], v[66:67] op_sel_hi:[1,0]
	v_pk_mul_f32 v[30:31], v[30:31], v[66:67] op_sel_hi:[1,0]
	v_pk_mul_f32 v[28:29], v[28:29], v[66:67] op_sel_hi:[1,0]
	v_pk_mul_f32 v[26:27], v[26:27], v[66:67] op_sel_hi:[1,0]
	v_pk_mul_f32 v[24:25], v[24:25], v[66:67] op_sel_hi:[1,0]
	v_pk_mul_f32 v[22:23], v[22:23], v[66:67] op_sel_hi:[1,0]
	v_pk_mul_f32 v[20:21], v[20:21], v[66:67] op_sel_hi:[1,0]
	v_pk_mul_f32 v[18:19], v[18:19], v[66:67] op_sel_hi:[1,0]
	v_pk_mul_f32 v[16:17], v[16:17], v[66:67] op_sel_hi:[1,0]
	v_pk_mul_f32 v[14:15], v[14:15], v[66:67] op_sel_hi:[1,0]
	v_pk_mul_f32 v[12:13], v[12:13], v[66:67] op_sel_hi:[1,0]
	v_pk_mul_f32 v[10:11], v[10:11], v[66:67] op_sel_hi:[1,0]
	v_pk_mul_f32 v[8:9], v[8:9], v[66:67] op_sel_hi:[1,0]
	v_pk_mul_f32 v[6:7], v[6:7], v[66:67] op_sel_hi:[1,0]
	v_pk_mul_f32 v[4:5], v[4:5], v[66:67] op_sel_hi:[1,0]
	v_pk_mul_f32 v[2:3], v[2:3], v[66:67] op_sel_hi:[1,0]
	v_pk_mul_f32 v[0:1], v[0:1], v[66:67] op_sel_hi:[1,0]
	v_mov_b32_e32 v65, v64
	v_mov_b32_e32 v66, v64
	v_mov_b32_e32 v67, v64
	v_mov_b32_e32 v68, v64
	v_mov_b32_e32 v69, v64
	v_mov_b32_e32 v70, v64
	v_mov_b32_e32 v71, v64
	v_mov_b32_e32 v72, v64
	v_mov_b32_e32 v73, v64
	v_mov_b32_e32 v74, v64
	v_mov_b32_e32 v75, v64
	v_mov_b32_e32 v76, v64
	v_mov_b32_e32 v77, v64
	v_mov_b32_e32 v78, v64
	v_mov_b32_e32 v79, v64
	v_mov_b32_e32 v96, v64
	v_mov_b32_e32 v97, v64
	v_mov_b32_e32 v98, v64
	v_mov_b32_e32 v99, v64
	v_mov_b32_e32 v100, v64
	v_mov_b32_e32 v101, v64
	v_mov_b32_e32 v102, v64
	v_mov_b32_e32 v103, v64
	v_mov_b32_e32 v104, v64
	v_mov_b32_e32 v105, v64
	v_mov_b32_e32 v106, v64
	v_mov_b32_e32 v107, v64
	v_mov_b32_e32 v108, v64
	v_mov_b32_e32 v109, v64
	v_mov_b32_e32 v110, v64
	v_mov_b32_e32 v111, v64
	s_branch .LBB0_413
.Lmy_x419:
	v_mov_b64_e32 v[64:65], v[96:97]
	v_mov_b64_e32 v[66:67], v[98:99]
	v_mov_b64_e32 v[68:69], v[100:101]
	v_mov_b64_e32 v[70:71], v[102:103]
	v_mov_b64_e32 v[72:73], v[104:105]
	v_mov_b64_e32 v[74:75], v[106:107]
	v_mov_b64_e32 v[76:77], v[108:109]
	v_mov_b64_e32 v[78:79], v[110:111]
.LBB0_419:
	ds_read_b128 v[96:99], v231 offset:9216
	ds_read_b128 v[144:147], v231 offset:13824
	s_waitcnt lgkmcnt(1)
	v_mfma_f32_32x32x16_bf16 v[128:143], v[96:99], v[174:177], v[64:79]
	ds_read_b128 v[148:151], v231 offset:9248
	v_exp_f32_e32 v206, v112
	v_exp_f32_e32 v207, v113
	v_exp_f32_e32 v112, v114
	v_exp_f32_e32 v113, v115
	s_waitcnt lgkmcnt(1)
	v_mfma_f32_32x32x16_bf16 v[96:111], v[144:147], v[174:177], v[64:79]
	ds_read_b128 v[152:155], v231 offset:13856
	v_exp_f32_e32 v114, v116
	v_exp_f32_e32 v115, v117
	s_waitcnt lgkmcnt(1)
	v_mfma_f32_32x32x16_bf16 v[128:143], v[148:151], v[170:173], v[128:143]
	ds_read_b128 v[144:147], v231 offset:9280
	v_exp_f32_e32 v116, v118
	v_exp_f32_e32 v117, v119
	s_waitcnt lgkmcnt(1)
	v_mfma_f32_32x32x16_bf16 v[96:111], v[152:155], v[170:173], v[96:111]
	ds_read_b128 v[190:193], v231 offset:13888
	s_waitcnt vmcnt(2)
	ds_write_b128 v232, v[178:181]
	s_waitcnt vmcnt(1)
	ds_write_b128 v232, v[182:185] offset:36864
	s_waitcnt vmcnt(0)
	ds_write_b128 v232, v[186:189] offset:46080
	v_cvt_pk_bf16_f32 v178, v206, v207
	v_cvt_pk_bf16_f32 v179, v112, v113
	v_cvt_pk_bf16_f32 v180, v114, v115
	v_cvt_pk_bf16_f32 v181, v116, v117
	s_waitcnt lgkmcnt(4)
; template <int DV, int PAR, bool KW = true, bool KL = true, bool VL = true>
; __device__ __forceinline__ void attn_iter_full(AttnState<DV>& S, int t, LAS unsigned char* lds) {
;     ...
;         if (i < 8) { if (i & 1) sn1 = MFMA32(fr[i % (PD + 1)], S.qr[i >> 1], sn1); else sn0 = MFMA32(fr[i % (PD + 1)], S.qr[i >> 1], sn0); }
;         else { const int j = i - 8; S.o[j % NDB] = MFMA32(fr[i % (PD + 1)], __builtin_bit_cast(bf16x8, pw[j / NDB]), S.o[j % NDB]); }
; #pragma unroll
;         for (int u = 0; u < NU; ++u) {
;             if (u * NS / NU != i) continue;
;             if (u < 20) {
;                 const int q = u / 5, r = u % 5;
;                 if (r < 4) { const int e = 8 * q + 2 * r;
;                     if (e < 16) { C0[e] = fast_exp2(C0[e]); C0[e + 1] = fast_exp2(C0[e + 1]); }
;                     else { C1[e - 16] = fast_exp2(C1[e - 16]); C1[e - 15] = fast_exp2(C1[e - 15]); } }
;                 else { if (q < 2) { const int b0 = 8 * q; pw[q].x = pk2(C0[b0], C0[b0 + 1]); pw[q].y = pk2(C0[b0 + 2], C0[b0 + 3]); pw[q].z = pk2(C0[b0 + 4], C0[b0 + 5]); pw[q].w = pk2(C0[b0 + 6], C0[b0 + 7]); }
;                        else { const int b0 = 8 * (q - 2); pw[q].x = pk2(C1[b0], C1[b0 + 1]); pw[q].y = pk2(C1[b0 + 2], C1[b0 + 3]); pw[q].z = pk2(C1[b0 + 4], C1[b0 + 5]); pw[q].w = pk2(C1[b0 + 6], C1[b0 + 7]); } }
;             } else if (u == 20) { ssum = C0 + C1; }
;             else if (u == 21) { const f32x4 a = (f32x4){ssum[0], ssum[1], ssum[2], ssum[3]} + (f32x4){ssum[4], ssum[5], ssum[6], ssum[7]} + (f32x4){ssum[8], ssum[9], ssum[10], ssum[11]} + (f32x4){ssum[12], ssum[13], ssum[14], ssum[15]};
;                 S.lsum += (a[0] + a[1]) + (a[2] + a[3]); }
;             else if (u == 22) { mxa = max3f(sn0[0], sn0[1], sn1[0]); mxb = max3f(sn0[2], sn0[3], sn1[1]); mxa = max3f(mxa, sn1[2], sn1[3]); }
;             else if (u < 26) { const int r = 4 * (u - 22); mxa = max3f(mxa, sn0[r], sn0[r + 1]); mxb = max3f(mxb, sn0[r + 2], sn0[r + 3]); mxa = max3f(mxa, sn1[r], sn1[r + 1]); mxb = max3f(mxb, sn1[r + 2], sn1[r + 3]); }
;             else { const float m = max2f(mxa, mxb); auto rr = __builtin_amdgcn_permlane32_swap(__float_as_uint(m), __float_as_uint(m), false, false); mx = max2f(__uint_as_float(rr[0]), __uint_as_float(rr[1])); }
;         }
;         __builtin_amdgcn_sched_barrier(0);
;     }
	v_mfma_f32_32x32x16_bf16 v[128:143], v[144:147], v[166:169], v[128:143]
	ds_read_b128 v[182:185], v231 offset:9312
	v_exp_f32_e32 v118, v120
	v_exp_f32_e32 v119, v121
	s_mov_b32 s2, 0x86000
	v_add_co_u32_e32 v120, vcc, s2, v204
	s_movk_i32 s2, 0x2000
	s_nop 0
	v_addc_co_u32_e32 v121, vcc, 0, v205, vcc
	v_add_co_u32_e32 v156, vcc, s2, v202
	s_mov_b32 s2, 0x8a000
	s_nop 0
	v_addc_co_u32_e32 v157, vcc, 0, v203, vcc
	v_add_co_u32_e32 v158, vcc, s2, v202
	ds_read_b128 v[186:189], v231 offset:13920
	s_nop 0
	v_addc_co_u32_e32 v159, vcc, 0, v203, vcc
	global_load_dwordx4 v[144:147], v[120:121], off
	global_load_dwordx4 v[148:151], v[156:157], off offset:256
	global_load_dwordx4 v[152:155], v[158:159], off offset:256
	s_waitcnt lgkmcnt(5)
	v_mfma_f32_32x32x16_bf16 v[96:111], v[190:193], v[166:169], v[96:111]
	v_exp_f32_e32 v190, v122
	v_exp_f32_e32 v191, v123
	s_waitcnt lgkmcnt(1)
	v_mfma_f32_32x32x16_bf16 v[128:143], v[182:185], v[162:165], v[128:143]
	ds_read_b128 v[120:123], v230 offset:18432
	v_exp_f32_e32 v192, v124
	v_exp_f32_e32 v193, v125
	s_waitcnt lgkmcnt(1)
	v_mfma_f32_32x32x16_bf16 v[96:111], v[186:189], v[162:165], v[96:111]
	ds_read_b128 v[182:185], v230 offset:23040
	v_exp_f32_e32 v196, v126
	v_exp_f32_e32 v197, v127
	s_waitcnt lgkmcnt(1)
	v_mfma_f32_32x32x16_bf16 v[48:63], v[120:123], v[178:181], v[48:63]
	ds_read_b128 v[124:127], v230 offset:27648
	v_cvt_pk_bf16_f32 v120, v118, v119
	v_cvt_pk_bf16_f32 v121, v190, v191
	v_cvt_pk_bf16_f32 v122, v192, v193
	v_cvt_pk_bf16_f32 v123, v196, v197
	v_exp_f32_e32 v198, v80
	v_exp_f32_e32 v199, v81
	s_waitcnt lgkmcnt(1)
	v_mfma_f32_32x32x16_bf16 v[32:47], v[182:185], v[178:181], v[32:47]
	ds_read_b128 v[186:189], v230 offset:32256
	v_exp_f32_e32 v182, v82
	v_exp_f32_e32 v183, v83
	s_waitcnt lgkmcnt(1)
	v_mfma_f32_32x32x16_bf16 v[16:31], v[124:127], v[178:181], v[16:31]
	ds_read_b128 v[80:83], v230 offset:18464
	v_exp_f32_e32 v184, v84
	v_exp_f32_e32 v185, v85
	s_waitcnt lgkmcnt(1)
	v_mfma_f32_32x32x16_bf16 v[0:15], v[186:189], v[178:181], v[0:15]
	ds_read_b128 v[124:127], v230 offset:23072
	v_exp_f32_e32 v186, v86
	v_exp_f32_e32 v187, v87
	s_waitcnt lgkmcnt(1)
	v_mfma_f32_32x32x16_bf16 v[48:63], v[80:83], v[120:123], v[48:63]
	ds_read_b128 v[84:87], v230 offset:27680
	v_cvt_pk_bf16_f32 v80, v198, v199
	v_cvt_pk_bf16_f32 v81, v182, v183
	v_cvt_pk_bf16_f32 v82, v184, v185
	v_cvt_pk_bf16_f32 v83, v186, v187
	s_waitcnt lgkmcnt(1)
	v_mfma_f32_32x32x16_bf16 v[32:47], v[124:127], v[120:123], v[32:47]
	ds_read_b128 v[178:181], v230 offset:32288
	v_exp_f32_e32 v188, v88
	v_exp_f32_e32 v189, v89
	s_waitcnt lgkmcnt(1)
	v_mfma_f32_32x32x16_bf16 v[16:31], v[84:87], v[120:123], v[16:31]
	ds_read_b128 v[124:127], v230 offset:18496
	v_exp_f32_e32 v202, v90
	v_exp_f32_e32 v203, v91
	s_waitcnt lgkmcnt(1)
	v_mfma_f32_32x32x16_bf16 v[0:15], v[178:181], v[120:123], v[0:15]
	ds_read_b128 v[84:87], v230 offset:23104
	v_exp_f32_e32 v178, v92
	v_exp_f32_e32 v179, v93
	s_waitcnt lgkmcnt(1)
	v_mfma_f32_32x32x16_bf16 v[48:63], v[124:127], v[80:83], v[48:63]
	ds_read_b128 v[88:91], v230 offset:27712
	v_exp_f32_e32 v124, v94
	v_exp_f32_e32 v125, v95
	v_cvt_pk_bf16_f32 v92, v188, v189
	v_cvt_pk_bf16_f32 v93, v202, v203
	v_cvt_pk_bf16_f32 v94, v178, v179
	v_cvt_pk_bf16_f32 v95, v124, v125
	s_waitcnt lgkmcnt(1)
	v_mfma_f32_32x32x16_bf16 v[32:47], v[84:87], v[80:83], v[32:47]
	ds_read_b128 v[120:123], v230 offset:32320
	v_add_f32_e64 v126, v178, v192
	v_add_f32_e64 v127, v179, v193
	v_add_f32_e64 v124, v124, v196
	v_add_f32_e64 v125, v125, v197
	v_pk_add_f32 v[178:179], v[202:203], v[190:191]
	v_pk_add_f32 v[118:119], v[188:189], v[118:119]
	v_pk_add_f32 v[114:115], v[184:185], v[114:115]
	v_pk_add_f32 v[180:181], v[198:199], v[206:207]
	v_pk_add_f32 v[116:117], v[186:187], v[116:117]
	v_pk_add_f32 v[112:113], v[182:183], v[112:113]
	s_waitcnt lgkmcnt(1)
	v_mfma_f32_32x32x16_bf16 v[16:31], v[88:91], v[80:83], v[16:31]
	v_add_f32_e64 v88, v112, v116
	v_add_f32_e64 v89, v113, v117
	v_add_f32_e64 v90, v180, v114
	v_add_f32_e64 v91, v181, v115
	v_add_f32_e64 v88, v178, v88
	v_add_f32_e64 v89, v179, v89
	v_pk_add_f32 v[90:91], v[118:119], v[90:91]
	v_pk_add_f32 v[88:89], v[124:125], v[88:89]
	v_pk_add_f32 v[90:91], v[126:127], v[90:91]
	ds_read_b128 v[84:87], v230 offset:18528
	v_pk_mov_b32 v[112:113], v[90:91], v[88:89] op_sel:[1,0]
	v_mov_b32_e32 v91, v89
	v_pk_add_f32 v[88:89], v[112:113], v[90:91]
	s_nop 0
	v_add_f32_e32 v88, v88, v89
	v_add_f32_e32 v160, v216, v88
	s_waitcnt lgkmcnt(1)
	v_mfma_f32_32x32x16_bf16 v[0:15], v[120:123], v[80:83], v[0:15]
	ds_read_b128 v[88:91], v230 offset:23136
	v_max3_f32 v80, v128, v129, v96
	v_max3_f32 v112, v130, v131, v97
	s_nop 0
	v_max3_f32 v113, v80, v98, v99
	s_waitcnt lgkmcnt(1)
	v_mfma_f32_32x32x16_bf16 v[48:63], v[84:87], v[92:95], v[48:63]
	ds_read_b128 v[80:83], v230 offset:27744
	v_max3_f32 v84, v113, v132, v133
	v_max3_f32 v85, v112, v134, v135
	s_nop 0
	v_max3_f32 v112, v84, v100, v101
	v_max3_f32 v113, v85, v102, v103
	s_waitcnt lgkmcnt(1)
	v_mfma_f32_32x32x16_bf16 v[32:47], v[88:91], v[92:95], v[32:47]
	ds_read_b128 v[84:87], v230 offset:32352
	v_max3_f32 v88, v112, v136, v137
	v_max3_f32 v89, v113, v138, v139
	s_nop 0
	v_max3_f32 v88, v88, v104, v105
	v_max3_f32 v89, v89, v106, v107
	s_waitcnt lgkmcnt(1)
	v_mfma_f32_32x32x16_bf16 v[16:31], v[80:83], v[92:95], v[16:31]
	v_max3_f32 v80, v88, v140, v141
	v_max3_f32 v81, v89, v142, v143
	s_nop 0
	v_max3_f32 v80, v80, v108, v109
	v_max3_f32 v81, v81, v110, v111
	s_waitcnt lgkmcnt(0)
	v_mfma_f32_32x32x16_bf16 v[0:15], v[84:87], v[92:95], v[0:15]
	v_max_f32_e32 v80, v80, v81
	s_nop 0
	v_mov_b32_e32 v81, v80
	s_nop 1
	v_permlane32_swap_b32_e32 v80, v81
	v_max_f32_e32 v80, v80, v81
	s_nop 0
	v_cmp_lt_f32_e32 vcc, s3, v80
	s_cbranch_vccz .LBB0_421
; __device__ __forceinline__ float fast_exp2(float x) { return __builtin_amdgcn_exp2f(x); }
; template <int DV, int PAR, bool KW = true, bool KL = true, bool VL = true>
; __device__ __forceinline__ void attn_iter_full(AttnState<DV>& S, int t, LAS unsigned char* lds) {
;     ...
;     if (__any(mx > 8.0f)) {
;         const float dl = fmaxf(mx, 0.f), alpha = fast_exp2(-dl);
;         S.mrun += dl; S.lsum *= alpha;
; #pragma unroll
;         for (int i = 0; i < 16; ++i) { sn0[i] -= dl; sn1[i] -= dl; S.negm[i] = -S.mrun; }
; #pragma unroll
;         for (int d = 0; d < NDB; ++d)
; #pragma unroll
;             for (int i = 0; i < 16; ++i) S.o[d][i] *= alpha;
;     }
	v_max_f32_e32 v64, v80, v80
	v_max_f32_e32 v66, 0, v64
	v_exp_f32_e64 v68, -v66
	v_add_f32_e32 v233, v233, v66
	v_xor_b32_e32 v64, 0x80000000, v233
	v_pk_add_f32 v[128:129], v[128:129], v[66:67] op_sel_hi:[1,0] neg_lo:[0,1] neg_hi:[0,1]
	v_mul_f32_e32 v160, v160, v68
	v_pk_add_f32 v[96:97], v[96:97], v[66:67] op_sel_hi:[1,0] neg_lo:[0,1] neg_hi:[0,1]
	v_pk_add_f32 v[130:131], v[130:131], v[66:67] op_sel_hi:[1,0] neg_lo:[0,1] neg_hi:[0,1]
	v_pk_add_f32 v[98:99], v[98:99], v[66:67] op_sel_hi:[1,0] neg_lo:[0,1] neg_hi:[0,1]
	v_pk_add_f32 v[132:133], v[132:133], v[66:67] op_sel_hi:[1,0] neg_lo:[0,1] neg_hi:[0,1]
	v_pk_add_f32 v[100:101], v[100:101], v[66:67] op_sel_hi:[1,0] neg_lo:[0,1] neg_hi:[0,1]
	v_pk_add_f32 v[134:135], v[134:135], v[66:67] op_sel_hi:[1,0] neg_lo:[0,1] neg_hi:[0,1]
	v_pk_add_f32 v[102:103], v[102:103], v[66:67] op_sel_hi:[1,0] neg_lo:[0,1] neg_hi:[0,1]
	v_pk_add_f32 v[136:137], v[136:137], v[66:67] op_sel_hi:[1,0] neg_lo:[0,1] neg_hi:[0,1]
	v_pk_add_f32 v[104:105], v[104:105], v[66:67] op_sel_hi:[1,0] neg_lo:[0,1] neg_hi:[0,1]
	v_pk_add_f32 v[138:139], v[138:139], v[66:67] op_sel_hi:[1,0] neg_lo:[0,1] neg_hi:[0,1]
	v_pk_add_f32 v[106:107], v[106:107], v[66:67] op_sel_hi:[1,0] neg_lo:[0,1] neg_hi:[0,1]
	v_pk_add_f32 v[140:141], v[140:141], v[66:67] op_sel_hi:[1,0] neg_lo:[0,1] neg_hi:[0,1]
	v_pk_add_f32 v[108:109], v[108:109], v[66:67] op_sel_hi:[1,0] neg_lo:[0,1] neg_hi:[0,1]
	v_pk_add_f32 v[142:143], v[142:143], v[66:67] op_sel_hi:[1,0] neg_lo:[0,1] neg_hi:[0,1]
	v_pk_add_f32 v[110:111], v[110:111], v[66:67] op_sel_hi:[1,0] neg_lo:[0,1] neg_hi:[0,1]
	v_pk_mul_f32 v[62:63], v[62:63], v[68:69] op_sel_hi:[1,0]
	v_pk_mul_f32 v[60:61], v[60:61], v[68:69] op_sel_hi:[1,0]
	v_pk_mul_f32 v[58:59], v[58:59], v[68:69] op_sel_hi:[1,0]
	v_pk_mul_f32 v[56:57], v[56:57], v[68:69] op_sel_hi:[1,0]
	v_pk_mul_f32 v[54:55], v[54:55], v[68:69] op_sel_hi:[1,0]
	v_pk_mul_f32 v[52:53], v[52:53], v[68:69] op_sel_hi:[1,0]
	v_pk_mul_f32 v[50:51], v[50:51], v[68:69] op_sel_hi:[1,0]
	v_pk_mul_f32 v[48:49], v[48:49], v[68:69] op_sel_hi:[1,0]
	v_pk_mul_f32 v[46:47], v[46:47], v[68:69] op_sel_hi:[1,0]
	v_pk_mul_f32 v[44:45], v[44:45], v[68:69] op_sel_hi:[1,0]
	v_pk_mul_f32 v[42:43], v[42:43], v[68:69] op_sel_hi:[1,0]
	v_pk_mul_f32 v[40:41], v[40:41], v[68:69] op_sel_hi:[1,0]
	v_pk_mul_f32 v[38:39], v[38:39], v[68:69] op_sel_hi:[1,0]
	v_pk_mul_f32 v[36:37], v[36:37], v[68:69] op_sel_hi:[1,0]
	v_pk_mul_f32 v[34:35], v[34:35], v[68:69] op_sel_hi:[1,0]
	v_pk_mul_f32 v[32:33], v[32:33], v[68:69] op_sel_hi:[1,0]
	v_pk_mul_f32 v[30:31], v[30:31], v[68:69] op_sel_hi:[1,0]
	v_pk_mul_f32 v[28:29], v[28:29], v[68:69] op_sel_hi:[1,0]
	v_pk_mul_f32 v[26:27], v[26:27], v[68:69] op_sel_hi:[1,0]
	v_pk_mul_f32 v[24:25], v[24:25], v[68:69] op_sel_hi:[1,0]
	v_pk_mul_f32 v[22:23], v[22:23], v[68:69] op_sel_hi:[1,0]
	v_pk_mul_f32 v[20:21], v[20:21], v[68:69] op_sel_hi:[1,0]
	v_pk_mul_f32 v[18:19], v[18:19], v[68:69] op_sel_hi:[1,0]
	v_pk_mul_f32 v[16:17], v[16:17], v[68:69] op_sel_hi:[1,0]
	v_pk_mul_f32 v[14:15], v[14:15], v[68:69] op_sel_hi:[1,0]
	v_pk_mul_f32 v[12:13], v[12:13], v[68:69] op_sel_hi:[1,0]
	v_pk_mul_f32 v[10:11], v[10:11], v[68:69] op_sel_hi:[1,0]
	v_pk_mul_f32 v[8:9], v[8:9], v[68:69] op_sel_hi:[1,0]
	v_pk_mul_f32 v[6:7], v[6:7], v[68:69] op_sel_hi:[1,0]
	v_pk_mul_f32 v[4:5], v[4:5], v[68:69] op_sel_hi:[1,0]
	v_pk_mul_f32 v[2:3], v[2:3], v[68:69] op_sel_hi:[1,0]
	v_pk_mul_f32 v[0:1], v[0:1], v[68:69] op_sel_hi:[1,0]
	v_mov_b32_e32 v65, v64
	v_mov_b32_e32 v66, v64
	v_mov_b32_e32 v67, v64
	v_mov_b32_e32 v68, v64
	v_mov_b32_e32 v69, v64
	v_mov_b32_e32 v70, v64
	v_mov_b32_e32 v71, v64
	v_mov_b32_e32 v72, v64
	v_mov_b32_e32 v73, v64
	v_mov_b32_e32 v74, v64
	v_mov_b32_e32 v75, v64
	v_mov_b32_e32 v76, v64
	v_mov_b32_e32 v77, v64
	v_mov_b32_e32 v78, v64
	v_mov_b32_e32 v79, v64

; template <int DV, int PAR, bool KW = true, bool KL = true, bool VL = true>
; __device__ __forceinline__ void attn_iter_full(AttnState<DV>& S, int t, LAS unsigned char* lds) {
;     ...
;     f32x16& C0 = PAR ? S.sd0 : S.sc0; f32x16& C1 = PAR ? S.sd1 : S.sc1; f32x16& sn0 = PAR ? S.sc0 : S.sd0; f32x16& sn1 = PAR ? S.sc1 : S.sd1;
;     sn0 = S.negm; sn1 = S.negm;
;     u32x4 pw[4]; float mxa = 0.f, mxb = 0.f, mx = 0.f; f32x16 ssum;
;     constexpr int PD = (DV == 64) ? 3 : 2; bf16x8 fr[PD + 1];
;     ...
; #pragma unroll
;     for (int i = 0; i < PD; ++i) fr[i] = AT_FRAG(i);
;     __builtin_amdgcn_sched_barrier(0);
; #pragma unroll
;     for (int i = 0; i < NS; ++i) {
;         if (i + PD < NS) fr[(i + PD) % (PD + 1)] = AT_FRAG(i + PD);
;         if (i == 3) {
;             if (KW) *(LAS u32x4*)(lds + AT_K0 + PAR * AT_KB + S.kl) = S.kreg;
;             LAS unsigned char* W = lds + AT_V0 + (PAR ^ 1) * AT_VB + S.vl; *(LAS u32x4*)W = S.vreg0; if (DV == 128) *(LAS u32x4*)(W + 64 * 144) = S.vreg1; }
;         if (i == 5) { if (KL) S.kreg = *(const u32x4*)(S.kg + (size_t)(t + 3) * 4096);
;             if (VL) { S.vreg0 = *(const u32x4*)(S.vg + (t + 2) * 64); if (DV == 128) S.vreg1 = *(const u32x4*)(S.vg + (size_t)64 * TK + (t + 2) * 64); } }
;         if (i < 8) { if (i & 1) sn1 = MFMA32(fr[i % (PD + 1)], S.qr[i >> 1], sn1); else sn0 = MFMA32(fr[i % (PD + 1)], S.qr[i >> 1], sn0); }
;         else { const int j = i - 8; S.o[j % NDB] = MFMA32(fr[i % (PD + 1)], __builtin_bit_cast(bf16x8, pw[j / NDB]), S.o[j % NDB]); }
; #pragma unroll
;         for (int u = 0; u < NU; ++u) {
;             if (u * NS / NU != i) continue;
;             if (u < 20) {
;                 const int q = u / 5, r = u % 5;
;                 if (r < 4) { const int e = 8 * q + 2 * r;
;                     if (e < 16) { C0[e] = fast_exp2(C0[e]); C0[e + 1] = fast_exp2(C0[e + 1]); }
;                     else { C1[e - 16] = fast_exp2(C1[e - 16]); C1[e - 15] = fast_exp2(C1[e - 15]); } }
;                 else { if (q < 2) { const int b0 = 8 * q; pw[q].x = pk2(C0[b0], C0[b0 + 1]); pw[q].y = pk2(C0[b0 + 2], C0[b0 + 3]); pw[q].z = pk2(C0[b0 + 4], C0[b0 + 5]); pw[q].w = pk2(C0[b0 + 6], C0[b0 + 7]); }
;                        else { const int b0 = 8 * (q - 2); pw[q].x = pk2(C1[b0], C1[b0 + 1]); pw[q].y = pk2(C1[b0 + 2], C1[b0 + 3]); pw[q].z = pk2(C1[b0 + 4], C1[b0 + 5]); pw[q].w = pk2(C1[b0 + 6], C1[b0 + 7]); } }
.LBB0_429:
.LBB0_430:
	s_barrier
	ds_read_b128 v[80:83], v234
	ds_read_b128 v[190:193], v234 offset:4608
	s_waitcnt lgkmcnt(1)
	v_mfma_f32_32x32x16_bf16 v[112:127], v[80:83], v[174:177], v[96:111]
	ds_read_b128 v[196:199], v234 offset:32
	v_exp_f32_e32 v216, v144
	v_exp_f32_e32 v217, v145
	v_exp_f32_e32 v144, v146
	v_exp_f32_e32 v145, v147
	s_waitcnt lgkmcnt(1)
	v_mfma_f32_32x32x16_bf16 v[80:95], v[190:193], v[174:177], v[96:111]
	ds_read_b128 v[242:245], v234 offset:4640
	v_exp_f32_e32 v146, v148
	v_exp_f32_e32 v147, v149
	s_waitcnt lgkmcnt(1)
	v_mfma_f32_32x32x16_bf16 v[112:127], v[196:199], v[170:173], v[112:127]
	ds_read_b128 v[190:193], v234 offset:64
	v_exp_f32_e32 v148, v150
	v_exp_f32_e32 v149, v151
	s_waitcnt lgkmcnt(1)
	v_mfma_f32_32x32x16_bf16 v[80:95], v[242:245], v[170:173], v[80:95]
	ds_read_b128 v[196:199], v234 offset:4672
	s_waitcnt vmcnt(2)
	ds_write_b128 v235, v[178:181] offset:9216
	s_waitcnt vmcnt(1)
	ds_write_b128 v235, v[182:185] offset:18432
	s_waitcnt vmcnt(0)
	ds_write_b128 v235, v[186:189] offset:27648
	v_cvt_pk_bf16_f32 v246, v216, v217
	v_cvt_pk_bf16_f32 v247, v144, v145
	v_cvt_pk_bf16_f32 v248, v146, v147
	v_cvt_pk_bf16_f32 v249, v148, v149
	s_waitcnt lgkmcnt(4)
	v_mfma_f32_32x32x16_bf16 v[112:127], v[190:193], v[166:169], v[112:127]
	ds_read_b128 v[242:245], v234 offset:96
	v_exp_f32_e32 v150, v152
	v_exp_f32_e32 v151, v153
	s_mov_b32 s2, 0x10e90000
	v_add_co_u32_e32 v152, vcc, s2, v210
	ds_read_b128 v[190:193], v234 offset:4704
	s_nop 0
	v_addc_co_u32_e32 v153, vcc, 0, v211, vcc
	global_load_dwordx4 v[186:189], v[152:153], off
	global_load_dwordx4 v[178:181], v[212:213], off offset:384
	global_load_dwordx4 v[182:185], v[214:215], off offset:384
	s_waitcnt lgkmcnt(5)
	v_mfma_f32_32x32x16_bf16 v[80:95], v[196:199], v[166:169], v[80:95]
	v_exp_f32_e32 v210, v154
	v_exp_f32_e32 v211, v155
	s_waitcnt lgkmcnt(1)
	v_mfma_f32_32x32x16_bf16 v[112:127], v[242:245], v[162:165], v[112:127]
	ds_read_b128 v[152:155], v233 offset:36864
	v_exp_f32_e32 v212, v156
	v_exp_f32_e32 v213, v157
	s_waitcnt lgkmcnt(1)
	v_mfma_f32_32x32x16_bf16 v[80:95], v[190:193], v[162:165], v[80:95]
	ds_read_b128 v[196:199], v233 offset:41472
	v_exp_f32_e32 v214, v158
	v_exp_f32_e32 v215, v159
	s_waitcnt lgkmcnt(1)
	v_mfma_f32_32x32x16_bf16 v[0:15], v[152:155], v[246:249], v[0:15]
	ds_read_b128 v[156:159], v233 offset:46080
	v_cvt_pk_bf16_f32 v152, v150, v151
	v_cvt_pk_bf16_f32 v153, v210, v211
	v_cvt_pk_bf16_f32 v154, v212, v213
	v_cvt_pk_bf16_f32 v155, v214, v215
	v_exp_f32_e32 v242, v128
	v_exp_f32_e32 v243, v129
	s_waitcnt lgkmcnt(1)
	v_mfma_f32_32x32x16_bf16 v[48:63], v[196:199], v[246:249], v[48:63]
	ds_read_b128 v[190:193], v233 offset:50688
	v_exp_f32_e32 v196, v130
	v_exp_f32_e32 v197, v131
	s_waitcnt lgkmcnt(1)
	v_mfma_f32_32x32x16_bf16 v[32:47], v[156:159], v[246:249], v[32:47]
	ds_read_b128 v[128:131], v233 offset:36896
	v_exp_f32_e32 v198, v132
	v_exp_f32_e32 v199, v133
	s_waitcnt lgkmcnt(1)
	v_mfma_f32_32x32x16_bf16 v[16:31], v[190:193], v[246:249], v[16:31]
	ds_read_b128 v[156:159], v233 offset:41504
	v_exp_f32_e32 v244, v134
	v_exp_f32_e32 v245, v135
	s_waitcnt lgkmcnt(1)
	v_mfma_f32_32x32x16_bf16 v[0:15], v[128:131], v[152:155], v[0:15]
	ds_read_b128 v[132:135], v233 offset:46112
	v_cvt_pk_bf16_f32 v128, v242, v243
	v_cvt_pk_bf16_f32 v129, v196, v197
	v_cvt_pk_bf16_f32 v130, v198, v199
	v_cvt_pk_bf16_f32 v131, v244, v245
	s_waitcnt lgkmcnt(1)
	v_mfma_f32_32x32x16_bf16 v[48:63], v[156:159], v[152:155], v[48:63]
	ds_read_b128 v[190:193], v233 offset:50720
	v_exp_f32_e32 v246, v136
	v_exp_f32_e32 v247, v137
	s_waitcnt lgkmcnt(1)
	v_mfma_f32_32x32x16_bf16 v[32:47], v[132:135], v[152:155], v[32:47]
	ds_read_b128 v[156:159], v233 offset:36928
	v_exp_f32_e32 v248, v138
	v_exp_f32_e32 v249, v139
	s_waitcnt lgkmcnt(1)
	v_mfma_f32_32x32x16_bf16 v[16:31], v[190:193], v[152:155], v[16:31]
	ds_read_b128 v[132:135], v233 offset:41536
	v_exp_f32_e32 v190, v140
	v_exp_f32_e32 v191, v141
	s_waitcnt lgkmcnt(1)
	v_mfma_f32_32x32x16_bf16 v[0:15], v[156:159], v[128:131], v[0:15]
	ds_read_b128 v[136:139], v233 offset:46144
	v_exp_f32_e32 v156, v142
	v_exp_f32_e32 v157, v143
	v_cvt_pk_bf16_f32 v140, v246, v247
	v_cvt_pk_bf16_f32 v141, v248, v249
	v_cvt_pk_bf16_f32 v142, v190, v191
	v_cvt_pk_bf16_f32 v143, v156, v157
	s_waitcnt lgkmcnt(1)
	v_mfma_f32_32x32x16_bf16 v[48:63], v[132:135], v[128:131], v[48:63]
	ds_read_b128 v[152:155], v233 offset:50752
	v_add_f32_e64 v158, v212, v190
	v_add_f32_e64 v159, v213, v191
	v_add_f32_e64 v156, v214, v156
	v_add_f32_e64 v157, v215, v157
	v_pk_add_f32 v[190:191], v[210:211], v[248:249]
	v_pk_add_f32 v[150:151], v[150:151], v[246:247]
	v_pk_add_f32 v[146:147], v[146:147], v[198:199]
	v_pk_add_f32 v[192:193], v[216:217], v[242:243]
	v_pk_add_f32 v[148:149], v[148:149], v[244:245]
	v_pk_add_f32 v[144:145], v[144:145], v[196:197]
	s_waitcnt lgkmcnt(1)
	v_mfma_f32_32x32x16_bf16 v[32:47], v[136:139], v[128:131], v[32:47]
	v_add_f32_e64 v136, v144, v148
	v_add_f32_e64 v137, v145, v149
	v_add_f32_e64 v138, v192, v146
	v_add_f32_e64 v139, v193, v147
	v_add_f32_e64 v136, v190, v136
	v_add_f32_e64 v137, v191, v137
	v_pk_add_f32 v[138:139], v[150:151], v[138:139]
	v_pk_add_f32 v[136:137], v[156:157], v[136:137]
	v_pk_add_f32 v[138:139], v[158:159], v[138:139]
	ds_read_b128 v[132:135], v233 offset:36960
	v_pk_mov_b32 v[144:145], v[138:139], v[136:137] op_sel:[1,0]
	v_mov_b32_e32 v139, v137
	v_pk_add_f32 v[136:137], v[144:145], v[138:139]
	s_nop 0
	v_add_f32_e32 v136, v136, v137
	v_add_f32_e32 v216, v237, v136
	s_waitcnt lgkmcnt(1)
	v_mfma_f32_32x32x16_bf16 v[16:31], v[152:155], v[128:131], v[16:31]
	ds_read_b128 v[136:139], v233 offset:41568
	v_max3_f32 v128, v112, v113, v80
	v_max3_f32 v144, v114, v115, v81
	s_nop 0
	v_max3_f32 v145, v128, v82, v83
	s_waitcnt lgkmcnt(1)
	v_mfma_f32_32x32x16_bf16 v[0:15], v[132:135], v[140:143], v[0:15]
	ds_read_b128 v[128:131], v233 offset:46176
	v_max3_f32 v132, v145, v116, v117
	v_max3_f32 v133, v144, v118, v119
	s_nop 0
	v_max3_f32 v144, v132, v84, v85
	v_max3_f32 v145, v133, v86, v87
	s_waitcnt lgkmcnt(1)
	v_mfma_f32_32x32x16_bf16 v[48:63], v[136:139], v[140:143], v[48:63]
	ds_read_b128 v[132:135], v233 offset:50784
	v_max3_f32 v136, v144, v120, v121
	v_max3_f32 v137, v145, v122, v123
	s_nop 0
	v_max3_f32 v136, v136, v88, v89
	v_max3_f32 v137, v137, v90, v91
	s_waitcnt lgkmcnt(1)
	v_mfma_f32_32x32x16_bf16 v[32:47], v[128:131], v[140:143], v[32:47]
	v_max3_f32 v128, v136, v124, v125
	v_max3_f32 v129, v137, v126, v127
	s_nop 0
	v_max3_f32 v128, v128, v92, v93
	v_max3_f32 v129, v129, v94, v95
	s_waitcnt lgkmcnt(0)
	v_mfma_f32_32x32x16_bf16 v[16:31], v[132:135], v[140:143], v[16:31]
	v_max_f32_e32 v128, v128, v129
	s_nop 0
	v_mov_b32_e32 v129, v128
	s_nop 1
	v_permlane32_swap_b32_e32 v128, v129
	v_max_f32_e32 v128, v128, v129
	s_nop 0
	v_cmp_lt_f32_e32 vcc, s3, v128
	s_cbranch_vccz .LBB0_426
; #define LAS __attribute__((address_space(3)))
; __device__ __forceinline__ float fast_exp2(float x) { return __builtin_amdgcn_exp2f(x); }
; #define MFMA32(a, b, c) __builtin_amdgcn_mfma_f32_32x32x16_bf16((a), (b), (c), 0, 0, 0)
; template <int DV, int PAR, bool KW = true, bool KL = true, bool VL = true>
; __device__ __forceinline__ void attn_iter_full(AttnState<DV>& S, int t, LAS unsigned char* lds) {
;     ...
;     sn0 = S.negm; sn1 = S.negm;
;     u32x4 pw[4]; float mxa = 0.f, mxb = 0.f, mx = 0.f; f32x16 ssum;
;     constexpr int PD = (DV == 64) ? 3 : 2; bf16x8 fr[PD + 1];
;     ...
; #pragma unroll
;     for (int i = 0; i < PD; ++i) fr[i] = AT_FRAG(i);
;     __builtin_amdgcn_sched_barrier(0);
; #pragma unroll
;     for (int i = 0; i < NS; ++i) {
;         if (i + PD < NS) fr[(i + PD) % (PD + 1)] = AT_FRAG(i + PD);
;         if (i == 3) {
;             if (KW) *(LAS u32x4*)(lds + AT_K0 + PAR * AT_KB + S.kl) = S.kreg;
;             LAS unsigned char* W = lds + AT_V0 + (PAR ^ 1) * AT_VB + S.vl; *(LAS u32x4*)W = S.vreg0; if (DV == 128) *(LAS u32x4*)(W + 64 * 144) = S.vreg1; }
;         if (i == 5) { if (KL) S.kreg = *(const u32x4*)(S.kg + (size_t)(t + 3) * 4096);
;             if (VL) { S.vreg0 = *(const u32x4*)(S.vg + (t + 2) * 64); if (DV == 128) S.vreg1 = *(const u32x4*)(S.vg + (size_t)64 * TK + (t + 2) * 64); } }
;         if (i < 8) { if (i & 1) sn1 = MFMA32(fr[i % (PD + 1)], S.qr[i >> 1], sn1); else sn0 = MFMA32(fr[i % (PD + 1)], S.qr[i >> 1], sn0); }
;         else { const int j = i - 8; S.o[j % NDB] = MFMA32(fr[i % (PD + 1)], __builtin_bit_cast(bf16x8, pw[j / NDB]), S.o[j % NDB]); }
; #pragma unroll
;         for (int u = 0; u < NU; ++u) {
;             if (u * NS / NU != i) continue;
;             if (u < 20) {
;                 const int q = u / 5, r = u % 5;
;                 if (r < 4) { const int e = 8 * q + 2 * r;
;                     if (e < 16) { C0[e] = fast_exp2(C0[e]); C0[e + 1] = fast_exp2(C0[e + 1]); }
;     ...
;     if (__any(mx > 8.0f)) {
;         const float dl = fmaxf(mx, 0.f), alpha = fast_exp2(-dl);
;         S.mrun += dl; S.lsum *= alpha;
; #pragma unroll
;         for (int i = 0; i < 16; ++i) { sn0[i] -= dl; sn1[i] -= dl; S.negm[i] = -S.mrun; }
; #pragma unroll
;         for (int d = 0; d < NDB; ++d)
; #pragma unroll
;             for (int i = 0; i < 16; ++i) S.o[d][i] *= alpha;
;     }
	v_max_f32_e32 v64, v128, v128
	v_max_f32_e32 v65, 0, v64
	v_exp_f32_e64 v66, -v65
	v_add_f32_e32 v236, v236, v65
	v_xor_b32_e32 v64, 0x80000000, v236
	v_sub_f32_e32 v127, v127, v65
	v_mul_f32_e32 v216, v216, v66
	v_sub_f32_e32 v126, v126, v65
	v_sub_f32_e32 v125, v125, v65
	v_sub_f32_e32 v124, v124, v65
	v_sub_f32_e32 v123, v123, v65
	v_sub_f32_e32 v122, v122, v65
	v_sub_f32_e32 v121, v121, v65
	v_sub_f32_e32 v120, v120, v65
	v_sub_f32_e32 v119, v119, v65
	v_sub_f32_e32 v118, v118, v65
	v_sub_f32_e32 v117, v117, v65
	v_sub_f32_e32 v116, v116, v65
	v_sub_f32_e32 v115, v115, v65
	v_sub_f32_e32 v114, v114, v65
	v_sub_f32_e32 v113, v113, v65
	v_sub_f32_e32 v112, v112, v65
	v_sub_f32_e32 v95, v95, v65
	v_sub_f32_e32 v94, v94, v65
	v_sub_f32_e32 v93, v93, v65
	v_sub_f32_e32 v92, v92, v65
	v_sub_f32_e32 v91, v91, v65
	v_sub_f32_e32 v90, v90, v65
	v_sub_f32_e32 v89, v89, v65
	v_sub_f32_e32 v88, v88, v65
	v_sub_f32_e32 v87, v87, v65
	v_sub_f32_e32 v86, v86, v65
	v_sub_f32_e32 v85, v85, v65
	v_sub_f32_e32 v84, v84, v65
	v_sub_f32_e32 v83, v83, v65
	v_sub_f32_e32 v82, v82, v65
	v_sub_f32_e32 v81, v81, v65
	v_sub_f32_e32 v80, v80, v65
	v_pk_mul_f32 v[14:15], v[14:15], v[66:67] op_sel_hi:[1,0]
	v_pk_mul_f32 v[12:13], v[12:13], v[66:67] op_sel_hi:[1,0]
	v_pk_mul_f32 v[10:11], v[10:11], v[66:67] op_sel_hi:[1,0]
	v_pk_mul_f32 v[8:9], v[8:9], v[66:67] op_sel_hi:[1,0]
	v_pk_mul_f32 v[6:7], v[6:7], v[66:67] op_sel_hi:[1,0]
	v_pk_mul_f32 v[4:5], v[4:5], v[66:67] op_sel_hi:[1,0]
	v_pk_mul_f32 v[2:3], v[2:3], v[66:67] op_sel_hi:[1,0]
	v_pk_mul_f32 v[0:1], v[0:1], v[66:67] op_sel_hi:[1,0]
	v_pk_mul_f32 v[62:63], v[62:63], v[66:67] op_sel_hi:[1,0]
	v_pk_mul_f32 v[60:61], v[60:61], v[66:67] op_sel_hi:[1,0]
	v_pk_mul_f32 v[58:59], v[58:59], v[66:67] op_sel_hi:[1,0]
	v_pk_mul_f32 v[56:57], v[56:57], v[66:67] op_sel_hi:[1,0]
	v_pk_mul_f32 v[54:55], v[54:55], v[66:67] op_sel_hi:[1,0]
	v_pk_mul_f32 v[52:53], v[52:53], v[66:67] op_sel_hi:[1,0]
	v_pk_mul_f32 v[50:51], v[50:51], v[66:67] op_sel_hi:[1,0]
	v_pk_mul_f32 v[48:49], v[48:49], v[66:67] op_sel_hi:[1,0]
	v_pk_mul_f32 v[46:47], v[46:47], v[66:67] op_sel_hi:[1,0]
	v_pk_mul_f32 v[44:45], v[44:45], v[66:67] op_sel_hi:[1,0]
	v_pk_mul_f32 v[42:43], v[42:43], v[66:67] op_sel_hi:[1,0]
	v_pk_mul_f32 v[40:41], v[40:41], v[66:67] op_sel_hi:[1,0]
	v_pk_mul_f32 v[38:39], v[38:39], v[66:67] op_sel_hi:[1,0]
	v_pk_mul_f32 v[36:37], v[36:37], v[66:67] op_sel_hi:[1,0]
	v_pk_mul_f32 v[34:35], v[34:35], v[66:67] op_sel_hi:[1,0]
	v_pk_mul_f32 v[32:33], v[32:33], v[66:67] op_sel_hi:[1,0]
	v_pk_mul_f32 v[30:31], v[30:31], v[66:67] op_sel_hi:[1,0]
	v_pk_mul_f32 v[28:29], v[28:29], v[66:67] op_sel_hi:[1,0]
	v_pk_mul_f32 v[26:27], v[26:27], v[66:67] op_sel_hi:[1,0]
	v_pk_mul_f32 v[24:25], v[24:25], v[66:67] op_sel_hi:[1,0]
	v_pk_mul_f32 v[22:23], v[22:23], v[66:67] op_sel_hi:[1,0]
	v_pk_mul_f32 v[20:21], v[20:21], v[66:67] op_sel_hi:[1,0]
	v_pk_mul_f32 v[18:19], v[18:19], v[66:67] op_sel_hi:[1,0]
	v_pk_mul_f32 v[16:17], v[16:17], v[66:67] op_sel_hi:[1,0]
	v_mov_b32_e32 v65, v64
	v_mov_b32_e32 v66, v64
	v_mov_b32_e32 v67, v64
	v_mov_b32_e32 v68, v64
	v_mov_b32_e32 v69, v64
	v_mov_b32_e32 v70, v64
	v_mov_b32_e32 v71, v64
	v_mov_b32_e32 v72, v64
	v_mov_b32_e32 v73, v64
	v_mov_b32_e32 v74, v64
	v_mov_b32_e32 v75, v64
	v_mov_b32_e32 v76, v64
	v_mov_b32_e32 v77, v64
	v_mov_b32_e32 v78, v64
	v_mov_b32_e32 v79, v64
	v_mov_b32_e32 v96, v64
	v_mov_b32_e32 v97, v64
	v_mov_b32_e32 v98, v64
	v_mov_b32_e32 v99, v64
	v_mov_b32_e32 v100, v64
	v_mov_b32_e32 v101, v64
	v_mov_b32_e32 v102, v64
	v_mov_b32_e32 v103, v64
	v_mov_b32_e32 v104, v64
	v_mov_b32_e32 v105, v64
	v_mov_b32_e32 v106, v64
	v_mov_b32_e32 v107, v64
	v_mov_b32_e32 v108, v64
	v_mov_b32_e32 v109, v64
	v_mov_b32_e32 v110, v64
	v_mov_b32_e32 v111, v64
	s_branch .LBB0_426
.Lmy_x432:
	v_mov_b64_e32 v[64:65], v[96:97]
	v_mov_b64_e32 v[66:67], v[98:99]
	v_mov_b64_e32 v[68:69], v[100:101]
	v_mov_b64_e32 v[70:71], v[102:103]
	v_mov_b64_e32 v[72:73], v[104:105]
	v_mov_b64_e32 v[74:75], v[106:107]
	v_mov_b64_e32 v[76:77], v[108:109]
	v_mov_b64_e32 v[78:79], v[110:111]
.LBB0_432:
	ds_read_b128 v[96:99], v234 offset:9216
	ds_read_b128 v[144:147], v234 offset:13824
	s_waitcnt lgkmcnt(1)
	v_mfma_f32_32x32x16_bf16 v[128:143], v[96:99], v[174:177], v[64:79]
	ds_read_b128 v[148:151], v234 offset:9248
	v_exp_f32_e32 v206, v112
	v_exp_f32_e32 v207, v113
	v_exp_f32_e32 v112, v114
	v_exp_f32_e32 v113, v115
	s_waitcnt lgkmcnt(1)
	v_mfma_f32_32x32x16_bf16 v[96:111], v[144:147], v[174:177], v[64:79]
	ds_read_b128 v[152:155], v234 offset:13856
	v_exp_f32_e32 v114, v116
	v_exp_f32_e32 v115, v117
	s_waitcnt lgkmcnt(1)
	v_mfma_f32_32x32x16_bf16 v[128:143], v[148:151], v[170:173], v[128:143]
	ds_read_b128 v[144:147], v234 offset:9280
	v_exp_f32_e32 v116, v118
	v_exp_f32_e32 v117, v119
	s_waitcnt lgkmcnt(1)
	v_mfma_f32_32x32x16_bf16 v[96:111], v[152:155], v[170:173], v[96:111]
	ds_read_b128 v[190:193], v234 offset:13888
	s_waitcnt vmcnt(2)
	ds_write_b128 v235, v[186:189]
	s_waitcnt vmcnt(1)
	ds_write_b128 v235, v[178:181] offset:36864
	s_waitcnt vmcnt(0)
	ds_write_b128 v235, v[182:185] offset:46080
	v_cvt_pk_bf16_f32 v178, v206, v207
	v_cvt_pk_bf16_f32 v179, v112, v113
	v_cvt_pk_bf16_f32 v180, v114, v115
	v_cvt_pk_bf16_f32 v181, v116, v117
	s_waitcnt lgkmcnt(4)
; template <int DV, int PAR, bool KW = true, bool KL = true, bool VL = true>
; __device__ __forceinline__ void attn_iter_full(AttnState<DV>& S, int t, LAS unsigned char* lds) {
;     ...
;         if (i < 8) { if (i & 1) sn1 = MFMA32(fr[i % (PD + 1)], S.qr[i >> 1], sn1); else sn0 = MFMA32(fr[i % (PD + 1)], S.qr[i >> 1], sn0); }
;         else { const int j = i - 8; S.o[j % NDB] = MFMA32(fr[i % (PD + 1)], __builtin_bit_cast(bf16x8, pw[j / NDB]), S.o[j % NDB]); }
; #pragma unroll
;         for (int u = 0; u < NU; ++u) {
;             if (u * NS / NU != i) continue;
;             if (u < 20) {
;                 const int q = u / 5, r = u % 5;
;                 if (r < 4) { const int e = 8 * q + 2 * r;
;                     if (e < 16) { C0[e] = fast_exp2(C0[e]); C0[e + 1] = fast_exp2(C0[e + 1]); }
;                     else { C1[e - 16] = fast_exp2(C1[e - 16]); C1[e - 15] = fast_exp2(C1[e - 15]); } }
;                 else { if (q < 2) { const int b0 = 8 * q; pw[q].x = pk2(C0[b0], C0[b0 + 1]); pw[q].y = pk2(C0[b0 + 2], C0[b0 + 3]); pw[q].z = pk2(C0[b0 + 4], C0[b0 + 5]); pw[q].w = pk2(C0[b0 + 6], C0[b0 + 7]); }
;                        else { const int b0 = 8 * (q - 2); pw[q].x = pk2(C1[b0], C1[b0 + 1]); pw[q].y = pk2(C1[b0 + 2], C1[b0 + 3]); pw[q].z = pk2(C1[b0 + 4], C1[b0 + 5]); pw[q].w = pk2(C1[b0 + 6], C1[b0 + 7]); } }
;             } else if (u == 20) { ssum = C0 + C1; }
;             else if (u == 21) { const f32x4 a = (f32x4){ssum[0], ssum[1], ssum[2], ssum[3]} + (f32x4){ssum[4], ssum[5], ssum[6], ssum[7]} + (f32x4){ssum[8], ssum[9], ssum[10], ssum[11]} + (f32x4){ssum[12], ssum[13], ssum[14], ssum[15]};
;                 S.lsum += (a[0] + a[1]) + (a[2] + a[3]); }
;             else if (u == 22) { mxa = max3f(sn0[0], sn0[1], sn1[0]); mxb = max3f(sn0[2], sn0[3], sn1[1]); mxa = max3f(mxa, sn1[2], sn1[3]); }
;             else if (u < 26) { const int r = 4 * (u - 22); mxa = max3f(mxa, sn0[r], sn0[r + 1]); mxb = max3f(mxb, sn0[r + 2], sn0[r + 3]); mxa = max3f(mxa, sn1[r], sn1[r + 1]); mxb = max3f(mxb, sn1[r + 2], sn1[r + 3]); }
;             else { const float m = max2f(mxa, mxb); auto rr = __builtin_amdgcn_permlane32_swap(__float_as_uint(m), __float_as_uint(m), false, false); mx = max2f(__uint_as_float(rr[0]), __uint_as_float(rr[1])); }
;         }
;         __builtin_amdgcn_sched_barrier(0);
;     }
	v_mfma_f32_32x32x16_bf16 v[128:143], v[144:147], v[166:169], v[128:143]
	ds_read_b128 v[182:185], v234 offset:9312
	v_exp_f32_e32 v118, v120
	v_exp_f32_e32 v119, v121
	s_mov_b32 s1, 0x86000
	v_add_co_u32_e32 v120, vcc, s1, v204
	s_movk_i32 s1, 0x2000
	s_nop 0
	v_addc_co_u32_e32 v121, vcc, 0, v205, vcc
	v_add_co_u32_e32 v156, vcc, s1, v202
	s_mov_b32 s1, 0x8a000
	s_nop 0
	v_addc_co_u32_e32 v157, vcc, 0, v203, vcc
	v_add_co_u32_e32 v158, vcc, s1, v202
	ds_read_b128 v[186:189], v234 offset:13920
	s_nop 0
	v_addc_co_u32_e32 v159, vcc, 0, v203, vcc
	global_load_dwordx4 v[144:147], v[120:121], off
	global_load_dwordx4 v[148:151], v[156:157], off offset:256
	global_load_dwordx4 v[152:155], v[158:159], off offset:256
	s_waitcnt lgkmcnt(5)
	v_mfma_f32_32x32x16_bf16 v[96:111], v[190:193], v[166:169], v[96:111]
	v_exp_f32_e32 v190, v122
	v_exp_f32_e32 v191, v123
	s_waitcnt lgkmcnt(1)
	v_mfma_f32_32x32x16_bf16 v[128:143], v[182:185], v[162:165], v[128:143]
	ds_read_b128 v[120:123], v233 offset:18432
	v_exp_f32_e32 v192, v124
	v_exp_f32_e32 v193, v125
	s_waitcnt lgkmcnt(1)
	v_mfma_f32_32x32x16_bf16 v[96:111], v[186:189], v[162:165], v[96:111]
	ds_read_b128 v[182:185], v233 offset:23040
	v_exp_f32_e32 v196, v126
	v_exp_f32_e32 v197, v127
	s_waitcnt lgkmcnt(1)
	v_mfma_f32_32x32x16_bf16 v[0:15], v[120:123], v[178:181], v[0:15]
	ds_read_b128 v[124:127], v233 offset:27648
	v_cvt_pk_bf16_f32 v120, v118, v119
	v_cvt_pk_bf16_f32 v121, v190, v191
	v_cvt_pk_bf16_f32 v122, v192, v193
	v_cvt_pk_bf16_f32 v123, v196, v197
	v_exp_f32_e32 v198, v80
	v_exp_f32_e32 v199, v81
	s_waitcnt lgkmcnt(1)
	v_mfma_f32_32x32x16_bf16 v[48:63], v[182:185], v[178:181], v[48:63]
	ds_read_b128 v[186:189], v233 offset:32256
	v_exp_f32_e32 v182, v82
	v_exp_f32_e32 v183, v83
	s_waitcnt lgkmcnt(1)
	v_mfma_f32_32x32x16_bf16 v[32:47], v[124:127], v[178:181], v[32:47]
	ds_read_b128 v[80:83], v233 offset:18464
	v_exp_f32_e32 v184, v84
	v_exp_f32_e32 v185, v85
	s_waitcnt lgkmcnt(1)
	v_mfma_f32_32x32x16_bf16 v[16:31], v[186:189], v[178:181], v[16:31]
	ds_read_b128 v[124:127], v233 offset:23072
	v_exp_f32_e32 v186, v86
	v_exp_f32_e32 v187, v87
	s_waitcnt lgkmcnt(1)
	v_mfma_f32_32x32x16_bf16 v[0:15], v[80:83], v[120:123], v[0:15]
	ds_read_b128 v[84:87], v233 offset:27680
	v_cvt_pk_bf16_f32 v80, v198, v199
	v_cvt_pk_bf16_f32 v81, v182, v183
	v_cvt_pk_bf16_f32 v82, v184, v185
	v_cvt_pk_bf16_f32 v83, v186, v187
	s_waitcnt lgkmcnt(1)
	v_mfma_f32_32x32x16_bf16 v[48:63], v[124:127], v[120:123], v[48:63]
	ds_read_b128 v[178:181], v233 offset:32288
	v_exp_f32_e32 v188, v88
	v_exp_f32_e32 v189, v89
	s_waitcnt lgkmcnt(1)
	v_mfma_f32_32x32x16_bf16 v[32:47], v[84:87], v[120:123], v[32:47]
	ds_read_b128 v[124:127], v233 offset:18496
	v_exp_f32_e32 v202, v90
	v_exp_f32_e32 v203, v91
	s_waitcnt lgkmcnt(1)
	v_mfma_f32_32x32x16_bf16 v[16:31], v[178:181], v[120:123], v[16:31]
	ds_read_b128 v[84:87], v233 offset:23104
	v_exp_f32_e32 v178, v92
	v_exp_f32_e32 v179, v93
	s_waitcnt lgkmcnt(1)
	v_mfma_f32_32x32x16_bf16 v[0:15], v[124:127], v[80:83], v[0:15]
	ds_read_b128 v[88:91], v233 offset:27712
	v_exp_f32_e32 v124, v94
	v_exp_f32_e32 v125, v95
	v_cvt_pk_bf16_f32 v92, v188, v189
	v_cvt_pk_bf16_f32 v93, v202, v203
	v_cvt_pk_bf16_f32 v94, v178, v179
	v_cvt_pk_bf16_f32 v95, v124, v125
	s_waitcnt lgkmcnt(1)
	v_mfma_f32_32x32x16_bf16 v[48:63], v[84:87], v[80:83], v[48:63]
	ds_read_b128 v[120:123], v233 offset:32320
	v_add_f32_e64 v126, v192, v178
	v_add_f32_e64 v127, v193, v179
	v_add_f32_e64 v124, v196, v124
	v_add_f32_e64 v125, v197, v125
	v_pk_add_f32 v[178:179], v[190:191], v[202:203]
	v_pk_add_f32 v[118:119], v[118:119], v[188:189]
	v_pk_add_f32 v[114:115], v[114:115], v[184:185]
	v_pk_add_f32 v[180:181], v[206:207], v[198:199]
	v_pk_add_f32 v[116:117], v[116:117], v[186:187]
	v_pk_add_f32 v[112:113], v[112:113], v[182:183]
	s_waitcnt lgkmcnt(1)
	v_mfma_f32_32x32x16_bf16 v[32:47], v[88:91], v[80:83], v[32:47]
	v_add_f32_e64 v88, v112, v116
	v_add_f32_e64 v89, v113, v117
	v_add_f32_e64 v90, v180, v114
	v_add_f32_e64 v91, v181, v115
	v_add_f32_e64 v88, v178, v88
	v_add_f32_e64 v89, v179, v89
	v_pk_add_f32 v[90:91], v[118:119], v[90:91]
	v_pk_add_f32 v[88:89], v[124:125], v[88:89]
	v_pk_add_f32 v[90:91], v[126:127], v[90:91]
	ds_read_b128 v[84:87], v233 offset:18528
	v_pk_mov_b32 v[112:113], v[90:91], v[88:89] op_sel:[1,0]
	v_mov_b32_e32 v91, v89
	v_pk_add_f32 v[88:89], v[112:113], v[90:91]
	s_nop 0
	v_add_f32_e32 v88, v88, v89
	v_add_f32_e32 v160, v216, v88
	s_waitcnt lgkmcnt(1)
	v_mfma_f32_32x32x16_bf16 v[16:31], v[120:123], v[80:83], v[16:31]
	ds_read_b128 v[88:91], v233 offset:23136
	v_max3_f32 v80, v128, v129, v96
	v_max3_f32 v112, v130, v131, v97
	s_nop 0
	v_max3_f32 v113, v80, v98, v99
	s_waitcnt lgkmcnt(1)
	v_mfma_f32_32x32x16_bf16 v[0:15], v[84:87], v[92:95], v[0:15]
	ds_read_b128 v[80:83], v233 offset:27744
	v_max3_f32 v84, v113, v132, v133
	v_max3_f32 v85, v112, v134, v135
	s_nop 0
	v_max3_f32 v112, v84, v100, v101
	v_max3_f32 v113, v85, v102, v103
	s_waitcnt lgkmcnt(1)
	v_mfma_f32_32x32x16_bf16 v[48:63], v[88:91], v[92:95], v[48:63]
	ds_read_b128 v[84:87], v233 offset:32352
	v_max3_f32 v88, v112, v136, v137
	v_max3_f32 v89, v113, v138, v139
	s_nop 0
	v_max3_f32 v88, v88, v104, v105
	v_max3_f32 v89, v89, v106, v107
	s_waitcnt lgkmcnt(1)
	v_mfma_f32_32x32x16_bf16 v[32:47], v[80:83], v[92:95], v[32:47]
	v_max3_f32 v80, v88, v140, v141
	v_max3_f32 v81, v89, v142, v143
	s_nop 0
	v_max3_f32 v80, v80, v108, v109
	v_max3_f32 v81, v81, v110, v111
	s_waitcnt lgkmcnt(0)
	v_mfma_f32_32x32x16_bf16 v[16:31], v[84:87], v[92:95], v[16:31]
	v_max_f32_e32 v80, v80, v81
	s_nop 0
	v_mov_b32_e32 v81, v80
	s_nop 1
	v_permlane32_swap_b32_e32 v80, v81
	v_max_f32_e32 v80, v80, v81
	s_nop 0
	v_cmp_lt_f32_e32 vcc, s3, v80
	s_cbranch_vccz .LBB0_434
; __device__ __forceinline__ float fast_exp2(float x) { return __builtin_amdgcn_exp2f(x); }
; template <int DV, int PAR, bool KW = true, bool KL = true, bool VL = true>
; __device__ __forceinline__ void attn_iter_full(AttnState<DV>& S, int t, LAS unsigned char* lds) {
;     ...
;     if (__any(mx > 8.0f)) {
;         const float dl = fmaxf(mx, 0.f), alpha = fast_exp2(-dl);
;         S.mrun += dl; S.lsum *= alpha;
; #pragma unroll
;         for (int i = 0; i < 16; ++i) { sn0[i] -= dl; sn1[i] -= dl; S.negm[i] = -S.mrun; }
; #pragma unroll
;         for (int d = 0; d < NDB; ++d)
; #pragma unroll
;             for (int i = 0; i < 16; ++i) S.o[d][i] *= alpha;
;     }
	v_max_f32_e32 v64, v80, v80
	v_max_f32_e32 v66, 0, v64
	v_exp_f32_e64 v68, -v66
	v_add_f32_e32 v236, v236, v66
	v_xor_b32_e32 v64, 0x80000000, v236
	v_pk_add_f32 v[128:129], v[128:129], v[66:67] op_sel_hi:[1,0] neg_lo:[0,1] neg_hi:[0,1]
	v_mul_f32_e32 v160, v160, v68
	v_pk_add_f32 v[96:97], v[96:97], v[66:67] op_sel_hi:[1,0] neg_lo:[0,1] neg_hi:[0,1]
	v_pk_add_f32 v[130:131], v[130:131], v[66:67] op_sel_hi:[1,0] neg_lo:[0,1] neg_hi:[0,1]
	v_pk_add_f32 v[98:99], v[98:99], v[66:67] op_sel_hi:[1,0] neg_lo:[0,1] neg_hi:[0,1]
	v_pk_add_f32 v[132:133], v[132:133], v[66:67] op_sel_hi:[1,0] neg_lo:[0,1] neg_hi:[0,1]
	v_pk_add_f32 v[100:101], v[100:101], v[66:67] op_sel_hi:[1,0] neg_lo:[0,1] neg_hi:[0,1]
	v_pk_add_f32 v[134:135], v[134:135], v[66:67] op_sel_hi:[1,0] neg_lo:[0,1] neg_hi:[0,1]
	v_pk_add_f32 v[102:103], v[102:103], v[66:67] op_sel_hi:[1,0] neg_lo:[0,1] neg_hi:[0,1]
	v_pk_add_f32 v[136:137], v[136:137], v[66:67] op_sel_hi:[1,0] neg_lo:[0,1] neg_hi:[0,1]
	v_pk_add_f32 v[104:105], v[104:105], v[66:67] op_sel_hi:[1,0] neg_lo:[0,1] neg_hi:[0,1]
	v_pk_add_f32 v[138:139], v[138:139], v[66:67] op_sel_hi:[1,0] neg_lo:[0,1] neg_hi:[0,1]
	v_pk_add_f32 v[106:107], v[106:107], v[66:67] op_sel_hi:[1,0] neg_lo:[0,1] neg_hi:[0,1]
	v_pk_add_f32 v[140:141], v[140:141], v[66:67] op_sel_hi:[1,0] neg_lo:[0,1] neg_hi:[0,1]
	v_pk_add_f32 v[108:109], v[108:109], v[66:67] op_sel_hi:[1,0] neg_lo:[0,1] neg_hi:[0,1]
	v_pk_add_f32 v[142:143], v[142:143], v[66:67] op_sel_hi:[1,0] neg_lo:[0,1] neg_hi:[0,1]
	v_pk_add_f32 v[110:111], v[110:111], v[66:67] op_sel_hi:[1,0] neg_lo:[0,1] neg_hi:[0,1]
	v_pk_mul_f32 v[14:15], v[14:15], v[68:69] op_sel_hi:[1,0]
	v_pk_mul_f32 v[12:13], v[12:13], v[68:69] op_sel_hi:[1,0]
	v_pk_mul_f32 v[10:11], v[10:11], v[68:69] op_sel_hi:[1,0]
	v_pk_mul_f32 v[8:9], v[8:9], v[68:69] op_sel_hi:[1,0]
	v_pk_mul_f32 v[6:7], v[6:7], v[68:69] op_sel_hi:[1,0]
	v_pk_mul_f32 v[4:5], v[4:5], v[68:69] op_sel_hi:[1,0]
	v_pk_mul_f32 v[2:3], v[2:3], v[68:69] op_sel_hi:[1,0]
	v_pk_mul_f32 v[0:1], v[0:1], v[68:69] op_sel_hi:[1,0]
	v_pk_mul_f32 v[62:63], v[62:63], v[68:69] op_sel_hi:[1,0]
	v_pk_mul_f32 v[60:61], v[60:61], v[68:69] op_sel_hi:[1,0]
	v_pk_mul_f32 v[58:59], v[58:59], v[68:69] op_sel_hi:[1,0]
	v_pk_mul_f32 v[56:57], v[56:57], v[68:69] op_sel_hi:[1,0]
	v_pk_mul_f32 v[54:55], v[54:55], v[68:69] op_sel_hi:[1,0]
	v_pk_mul_f32 v[52:53], v[52:53], v[68:69] op_sel_hi:[1,0]
	v_pk_mul_f32 v[50:51], v[50:51], v[68:69] op_sel_hi:[1,0]
	v_pk_mul_f32 v[48:49], v[48:49], v[68:69] op_sel_hi:[1,0]
	v_pk_mul_f32 v[46:47], v[46:47], v[68:69] op_sel_hi:[1,0]
	v_pk_mul_f32 v[44:45], v[44:45], v[68:69] op_sel_hi:[1,0]
	v_pk_mul_f32 v[42:43], v[42:43], v[68:69] op_sel_hi:[1,0]
	v_pk_mul_f32 v[40:41], v[40:41], v[68:69] op_sel_hi:[1,0]
	v_pk_mul_f32 v[38:39], v[38:39], v[68:69] op_sel_hi:[1,0]
	v_pk_mul_f32 v[36:37], v[36:37], v[68:69] op_sel_hi:[1,0]
	v_pk_mul_f32 v[34:35], v[34:35], v[68:69] op_sel_hi:[1,0]
	v_pk_mul_f32 v[32:33], v[32:33], v[68:69] op_sel_hi:[1,0]
	v_pk_mul_f32 v[30:31], v[30:31], v[68:69] op_sel_hi:[1,0]
	v_pk_mul_f32 v[28:29], v[28:29], v[68:69] op_sel_hi:[1,0]
	v_pk_mul_f32 v[26:27], v[26:27], v[68:69] op_sel_hi:[1,0]
	v_pk_mul_f32 v[24:25], v[24:25], v[68:69] op_sel_hi:[1,0]
	v_pk_mul_f32 v[22:23], v[22:23], v[68:69] op_sel_hi:[1,0]
	v_pk_mul_f32 v[20:21], v[20:21], v[68:69] op_sel_hi:[1,0]
	v_pk_mul_f32 v[18:19], v[18:19], v[68:69] op_sel_hi:[1,0]
	v_pk_mul_f32 v[16:17], v[16:17], v[68:69] op_sel_hi:[1,0]
	v_mov_b32_e32 v65, v64
	v_mov_b32_e32 v66, v64
	v_mov_b32_e32 v67, v64
	v_mov_b32_e32 v68, v64
	v_mov_b32_e32 v69, v64
	v_mov_b32_e32 v70, v64
	v_mov_b32_e32 v71, v64
	v_mov_b32_e32 v72, v64
	v_mov_b32_e32 v73, v64
	v_mov_b32_e32 v74, v64
	v_mov_b32_e32 v75, v64
	v_mov_b32_e32 v76, v64
	v_mov_b32_e32 v77, v64
	v_mov_b32_e32 v78, v64
	v_mov_b32_e32 v79, v64
